# opt6
# speedup vs baseline: 1.0416x; 1.0416x over previous
; __device__ __forceinline__ void gemm_phase(const Ctx& cx, const GemmArgs& g_, char* shm) {
;     ...
;           for (int m = 0; m < 4; ++m) {
;             const int n0 = brow + ai * 128 + wr * 64 + m * 16 + fq * 4;
;             f32x4 a = acc[ai][bj][m][n];
;             if (g.epi == EPI_PROJ || g.epi == EPI_RELU2) { a[0] *= rs; a[1] *= rs; a[2] *= rs; a[3] *= rs; }
;             if (g.epi == EPI_PROJ) {
;               if (n0 >= C_GLAX) {
;                 const int i = n0 - C_GLAX;
;                 const float4 b4 = *(const float4*)(g.hin + i);
;                 float xs[4] = {a[0] + b4.x, a[1] + b4.y, a[2] + b4.z, a[3] + b4.w};
; #pragma unroll
;                 for (int j = 0; j < 4; ++j)
;                   xs[j] = (fminf(xs[j], 0.f) - __logf(1.0f + __expf(-fabsf(xs[j])))) * (1.0f / 16.0f);
;                 *(float4*)(g.f32buf + (size_t)tok * 1024 + i) = make_float4(xs[0], xs[1], xs[2], xs[3]);
;               } else {
;                 float o0 = a[0], o1 = a[1], o2 = a[2], o3 = a[3];
;                 const bool r128 = (n0 >= C_DSAQ && n0 < C_HGQ) || (n0 >= C_DSAK && n0 < C_DSAV);
;                 const bool r64 = (n0 >= C_IDXQ && n0 < C_GLAA);
;                 if (r128 || r64) {
.LBB0_248:
	s_cmp_eq_u32 s38, 5
	s_cbranch_scc1 .Lmy_fast_relu
	s_cmp_lt_u32 s38, 4
	s_cselect_b32 s0, 1, 0
	s_cmp_gt_u32 s38, 0
	s_cselect_b32 s3, 1, 0
	s_and_b32 s0, s0, s3
	s_cmp_lg_u32 s0, 0
	s_cbranch_scc1 .Lmy_fast_br
	s_cmp_lg_u32 s38, 0
	s_cbranch_scc1 .Lmy_slow_epi
	s_cmpk_lt_u32 s2, 0x1800
	s_cbranch_scc1 .Lmy_fast_proj
	s_cmpk_lt_u32 s2, 0x2000
	s_cbranch_scc1 .Lmy_slow_epi
	s_cmpk_lt_u32 s2, 0x5800
	s_cbranch_scc1 .Lmy_fast_proj
	s_branch .Lmy_slow_epi

; __device__ __forceinline__ float b2f(u16 b) { return __uint_as_float(((uint32_t)b) << 16); }
; __device__ __forceinline__ float sigmoidf_(float x) { return 1.0f / (1.0f + __expf(-x)); }
; __device__ __forceinline__ void gemm_phase(const Ctx& cx, const GemmArgs& g_, char* shm) {
;     ...
;               const uint2 gv = *(const uint2*)(g.gate + (size_t)tok * NP + n0);
;               float v0 = sigmoidf_(b2f((u16)(gv.x & 0xffff))) * a[0], v1 = sigmoidf_(b2f((u16)(gv.x >> 16))) * a[1];
;               float v2 = sigmoidf_(b2f((u16)(gv.y & 0xffff))) * a[2], v3 = sigmoidf_(b2f((u16)(gv.y >> 16))) * a[3];
;               uint2* mp = (uint2*)(g.outb + (size_t)tok * DM + n0);
;               if (g.epi != EPI_BR0) {
.Lmy_fast_br:
	v_or_b32_e32 v194, s4, v168
	v_add_u32_e32 v186, s2, v169
	v_add_u32_e32 v188, v186, v170
	v_ashrrev_i32_e32 v189, 31, v188
	v_mad_i64_i32 v[184:185], s[6:7], v194, s39, 0
	v_lshl_add_u64 v[184:185], v[184:185], 1, s[20:21]
	v_lshl_add_u64 v[184:185], v[188:189], 1, v[184:185]
	s_lshl_b32 s6, s39, 4
	s_sub_i32 s6, 64, s6
	v_and_b32_e32 v192, 8, v168
	v_cmp_ne_u32_e32 vcc, 0, v192
	v_mov_b32_e32 v193, s6
	s_nop 1
	v_cndmask_b32_e32 v192, 0, v193, vcc
	v_cndmask_b32_e64 v193, 0, -1, vcc
	v_lshl_add_u64 v[184:185], v[184:185], 0, v[192:193]
	s_lshl_b32 s6, s39, 4
	s_mov_b32 s7, 0
	s_lshl_b32 s8, s39, 5
	s_mov_b32 s9, 0
	s_lshl_b32 s10, s39, 8
	s_mov_b32 s11, 0
	v_add_u32_e32 v186, v186, v0
	v_ashrrev_i32_e32 v187, 31, v186
	v_mov_b32_e32 v188, v184
	v_mov_b32_e32 v189, v185
	v_lshl_add_u64 v[190:191], v[188:189], 0, s[6:7]
	v_add_u32_e32 v195, 0, v194
	v_mov_b64_e32 v[244:245], s[22:23]
	v_mad_i64_i32 v[244:245], s[4:5], v195, s76, v[244:245]
	v_lshl_add_u64 v[244:245], v[186:187], 1, v[244:245]
	global_load_dwordx2 v[196:197], v[244:245], off offset:0
	global_load_dwordx2 v[198:199], v[244:245], off offset:32
	global_load_dwordx2 v[200:201], v[244:245], off offset:64
	global_load_dwordx2 v[202:203], v[244:245], off offset:96
	global_load_dwordx2 v[204:205], v[244:245], off offset:256
	global_load_dwordx2 v[206:207], v[244:245], off offset:288
	global_load_dwordx2 v[208:209], v[244:245], off offset:320
	global_load_dwordx2 v[210:211], v[244:245], off offset:352
	s_and_b64 vcc, exec, s[44:45]
	s_cbranch_vccz .Lmy_br_nopv_ld_0
	v_mov_b32_e32 v192, v195
	v_ashrrev_i32_e32 v193, 31, v195
	v_lshlrev_b64 v[192:193], 12, v[192:193]
	v_lshl_add_u64 v[192:193], s[20:21], 0, v[192:193]
	v_lshl_add_u64 v[192:193], v[186:187], 1, v[192:193]
	global_load_dwordx2 v[212:213], v[192:193], off offset:0
	global_load_dwordx2 v[214:215], v[192:193], off offset:32
	global_load_dwordx2 v[216:217], v[192:193], off offset:64
	global_load_dwordx2 v[218:219], v[192:193], off offset:96
	global_load_dwordx2 v[220:221], v[192:193], off offset:256
	global_load_dwordx2 v[222:223], v[192:193], off offset:288
	global_load_dwordx2 v[224:225], v[192:193], off offset:320
	global_load_dwordx2 v[226:227], v[192:193], off offset:352
.Lmy_br_nopv_ld_0:
	s_waitcnt vmcnt(0)
	v_lshlrev_b32_e32 v228, 16, v196
	v_mul_f32_e32 v228, 0xbfb8aa3b, v228
	v_exp_f32_e32 v229, v228
	s_nop 0
	v_add_f32_e32 v229, 1.0, v229
	s_nop 0
	v_div_scale_f32 v230, s[2:3], v229, v229, 1.0
	v_rcp_f32_e32 v231, v230
	s_nop 0
	v_fma_f32 v232, -v230, v231, 1.0
	v_fmac_f32_e32 v231, v232, v231
	v_div_scale_f32 v233, vcc, 1.0, v229, 1.0
	v_mul_f32_e32 v234, v233, v231
	v_fma_f32 v235, -v230, v234, v233
	v_fmac_f32_e32 v234, v235, v231
	v_fma_f32 v230, -v230, v234, v233
	v_div_fmas_f32 v230, v230, v231, v234
	v_div_fixup_f32 v230, v230, v229, 1.0
	v_mul_f32_e32 v128, v128, v230
	v_and_b32_e32 v228, 0xffff0000, v196
	v_mul_f32_e32 v228, 0xbfb8aa3b, v228
	v_exp_f32_e32 v229, v228
	s_nop 0
	v_add_f32_e32 v229, 1.0, v229
	s_nop 0
	v_div_scale_f32 v230, s[2:3], v229, v229, 1.0
	v_rcp_f32_e32 v231, v230
	s_nop 0
	v_fma_f32 v232, -v230, v231, 1.0
	v_fmac_f32_e32 v231, v232, v231
	v_div_scale_f32 v233, vcc, 1.0, v229, 1.0
	v_mul_f32_e32 v234, v233, v231
	v_fma_f32 v235, -v230, v234, v233
	v_fmac_f32_e32 v234, v235, v231
	v_fma_f32 v230, -v230, v234, v233
	v_div_fmas_f32 v230, v230, v231, v234
	v_div_fixup_f32 v230, v230, v229, 1.0
	v_mul_f32_e32 v129, v129, v230
	v_lshlrev_b32_e32 v228, 16, v197
	v_mul_f32_e32 v228, 0xbfb8aa3b, v228
	v_exp_f32_e32 v229, v228
	s_nop 0
	v_add_f32_e32 v229, 1.0, v229
	s_nop 0
	v_div_scale_f32 v230, s[2:3], v229, v229, 1.0
	v_rcp_f32_e32 v231, v230
	s_nop 0
	v_fma_f32 v232, -v230, v231, 1.0
	v_fmac_f32_e32 v231, v232, v231
	v_div_scale_f32 v233, vcc, 1.0, v229, 1.0
	v_mul_f32_e32 v234, v233, v231
	v_fma_f32 v235, -v230, v234, v233
	v_fmac_f32_e32 v234, v235, v231
	v_fma_f32 v230, -v230, v234, v233
	v_div_fmas_f32 v230, v230, v231, v234
	v_div_fixup_f32 v230, v230, v229, 1.0
	v_mul_f32_e32 v130, v130, v230
	v_and_b32_e32 v228, 0xffff0000, v197
	v_mul_f32_e32 v228, 0xbfb8aa3b, v228
	v_exp_f32_e32 v229, v228
	s_nop 0
	v_add_f32_e32 v229, 1.0, v229
	s_nop 0
	v_div_scale_f32 v230, s[2:3], v229, v229, 1.0
	v_rcp_f32_e32 v231, v230
	s_nop 0
	v_fma_f32 v232, -v230, v231, 1.0
	v_fmac_f32_e32 v231, v232, v231
	v_div_scale_f32 v233, vcc, 1.0, v229, 1.0
	v_mul_f32_e32 v234, v233, v231
	v_fma_f32 v235, -v230, v234, v233
	v_fmac_f32_e32 v234, v235, v231
	v_fma_f32 v230, -v230, v234, v233
	v_div_fmas_f32 v230, v230, v231, v234
	v_div_fixup_f32 v230, v230, v229, 1.0
	v_mul_f32_e32 v131, v131, v230
	v_lshlrev_b32_e32 v228, 16, v198
	v_mul_f32_e32 v228, 0xbfb8aa3b, v228
	v_exp_f32_e32 v229, v228
	s_nop 0
	v_add_f32_e32 v229, 1.0, v229
	s_nop 0
	v_div_scale_f32 v230, s[2:3], v229, v229, 1.0
	v_rcp_f32_e32 v231, v230
	s_nop 0
	v_fma_f32 v232, -v230, v231, 1.0
	v_fmac_f32_e32 v231, v232, v231
	v_div_scale_f32 v233, vcc, 1.0, v229, 1.0
	v_mul_f32_e32 v234, v233, v231
	v_fma_f32 v235, -v230, v234, v233
	v_fmac_f32_e32 v234, v235, v231
	v_fma_f32 v230, -v230, v234, v233
	v_div_fmas_f32 v230, v230, v231, v234
	v_div_fixup_f32 v230, v230, v229, 1.0
	v_mul_f32_e32 v124, v124, v230
	v_and_b32_e32 v228, 0xffff0000, v198
	v_mul_f32_e32 v228, 0xbfb8aa3b, v228
	v_exp_f32_e32 v229, v228
	s_nop 0
	v_add_f32_e32 v229, 1.0, v229
	s_nop 0
	v_div_scale_f32 v230, s[2:3], v229, v229, 1.0
	v_rcp_f32_e32 v231, v230
	s_nop 0
	v_fma_f32 v232, -v230, v231, 1.0
	v_fmac_f32_e32 v231, v232, v231
	v_div_scale_f32 v233, vcc, 1.0, v229, 1.0
	v_mul_f32_e32 v234, v233, v231
	v_fma_f32 v235, -v230, v234, v233
	v_fmac_f32_e32 v234, v235, v231
	v_fma_f32 v230, -v230, v234, v233
	v_div_fmas_f32 v230, v230, v231, v234
	v_div_fixup_f32 v230, v230, v229, 1.0
	v_mul_f32_e32 v125, v125, v230
	v_lshlrev_b32_e32 v228, 16, v199
	v_mul_f32_e32 v228, 0xbfb8aa3b, v228
	v_exp_f32_e32 v229, v228
	s_nop 0
	v_add_f32_e32 v229, 1.0, v229
	s_nop 0
	v_div_scale_f32 v230, s[2:3], v229, v229, 1.0
	v_rcp_f32_e32 v231, v230
	s_nop 0
	v_fma_f32 v232, -v230, v231, 1.0
	v_fmac_f32_e32 v231, v232, v231
	v_div_scale_f32 v233, vcc, 1.0, v229, 1.0
	v_mul_f32_e32 v234, v233, v231
	v_fma_f32 v235, -v230, v234, v233
	v_fmac_f32_e32 v234, v235, v231
	v_fma_f32 v230, -v230, v234, v233
	v_div_fmas_f32 v230, v230, v231, v234
	v_div_fixup_f32 v230, v230, v229, 1.0
	v_mul_f32_e32 v126, v126, v230
	v_and_b32_e32 v228, 0xffff0000, v199
	v_mul_f32_e32 v228, 0xbfb8aa3b, v228
	v_exp_f32_e32 v229, v228
	s_nop 0
	v_add_f32_e32 v229, 1.0, v229
	s_nop 0
	v_div_scale_f32 v230, s[2:3], v229, v229, 1.0
	v_rcp_f32_e32 v231, v230
	s_nop 0
	v_fma_f32 v232, -v230, v231, 1.0
	v_fmac_f32_e32 v231, v232, v231
	v_div_scale_f32 v233, vcc, 1.0, v229, 1.0
	v_mul_f32_e32 v234, v233, v231
	v_fma_f32 v235, -v230, v234, v233
	v_fmac_f32_e32 v234, v235, v231
	v_fma_f32 v230, -v230, v234, v233
	v_div_fmas_f32 v230, v230, v231, v234
	v_div_fixup_f32 v230, v230, v229, 1.0
	v_mul_f32_e32 v127, v127, v230
	s_and_b64 vcc, exec, s[44:45]
	s_cbranch_vccz .Lmy_br_nopv_add_0_0_0
; __device__ __forceinline__ float b2f(u16 b) { return __uint_as_float(((uint32_t)b) << 16); }
; __device__ __forceinline__ float sigmoidf_(float x) { return 1.0f / (1.0f + __expf(-x)); }
; __device__ __forceinline__ void gemm_phase(const Ctx& cx, const GemmArgs& g_, char* shm) {
;     ...
;               const uint2 gv = *(const uint2*)(g.gate + (size_t)tok * NP + n0);
;               float v0 = sigmoidf_(b2f((u16)(gv.x & 0xffff))) * a[0], v1 = sigmoidf_(b2f((u16)(gv.x >> 16))) * a[1];
;               float v2 = sigmoidf_(b2f((u16)(gv.y & 0xffff))) * a[2], v3 = sigmoidf_(b2f((u16)(gv.y >> 16))) * a[3];
;               uint2* mp = (uint2*)(g.outb + (size_t)tok * DM + n0);
;               if (g.epi != EPI_BR0) {
;                 const uint2 pv = *mp;
;                 v0 += b2f((u16)(pv.x & 0xffff)); v1 += b2f((u16)(pv.x >> 16));
;                 v2 += b2f((u16)(pv.y & 0xffff)); v3 += b2f((u16)(pv.y >> 16));
;               }
;               uint2 o; o.x = pack2(v0, v1); o.y = pack2(v2, v3);
;               *mp = o;
	v_lshlrev_b32_e32 v228, 16, v212
	v_add_f32_e32 v128, v128, v228
	v_and_b32_e32 v228, 0xffff0000, v212
	v_add_f32_e32 v129, v129, v228
	v_lshlrev_b32_e32 v228, 16, v213
	v_add_f32_e32 v130, v130, v228
	v_and_b32_e32 v228, 0xffff0000, v213
	v_add_f32_e32 v131, v131, v228
	v_lshlrev_b32_e32 v228, 16, v214
	v_add_f32_e32 v124, v124, v228
	v_and_b32_e32 v228, 0xffff0000, v214
	v_add_f32_e32 v125, v125, v228
	v_lshlrev_b32_e32 v228, 16, v215
	v_add_f32_e32 v126, v126, v228
	v_and_b32_e32 v228, 0xffff0000, v215
	v_add_f32_e32 v127, v127, v228
.Lmy_br_nopv_add_0_0_0:
	v_cvt_pk_bf16_f32 v236, v128, v129
	v_cvt_pk_bf16_f32 v237, v130, v131
	v_cvt_pk_bf16_f32 v238, v124, v125
	v_cvt_pk_bf16_f32 v239, v126, v127
	s_nop 1
	v_permlane16_swap_b32_e32 v236, v238
	v_permlane16_swap_b32_e32 v237, v239
	v_lshlrev_b32_e32 v228, 16, v200
	v_mul_f32_e32 v228, 0xbfb8aa3b, v228
	v_exp_f32_e32 v229, v228
	s_nop 0
	v_add_f32_e32 v229, 1.0, v229
	s_nop 0
	v_div_scale_f32 v230, s[2:3], v229, v229, 1.0
	v_rcp_f32_e32 v231, v230
	s_nop 0
	v_fma_f32 v232, -v230, v231, 1.0
	v_fmac_f32_e32 v231, v232, v231
	v_div_scale_f32 v233, vcc, 1.0, v229, 1.0
	v_mul_f32_e32 v234, v233, v231
	v_fma_f32 v235, -v230, v234, v233
	v_fmac_f32_e32 v234, v235, v231
	v_fma_f32 v230, -v230, v234, v233
	v_div_fmas_f32 v230, v230, v231, v234
	v_div_fixup_f32 v230, v230, v229, 1.0
	v_mul_f32_e32 v120, v120, v230
	v_and_b32_e32 v228, 0xffff0000, v200
	v_mul_f32_e32 v228, 0xbfb8aa3b, v228
	v_exp_f32_e32 v229, v228
	s_nop 0
	v_add_f32_e32 v229, 1.0, v229
	s_nop 0
	v_div_scale_f32 v230, s[2:3], v229, v229, 1.0
	v_rcp_f32_e32 v231, v230
	s_nop 0
	v_fma_f32 v232, -v230, v231, 1.0
	v_fmac_f32_e32 v231, v232, v231
	v_div_scale_f32 v233, vcc, 1.0, v229, 1.0
	v_mul_f32_e32 v234, v233, v231
	v_fma_f32 v235, -v230, v234, v233
	v_fmac_f32_e32 v234, v235, v231
	v_fma_f32 v230, -v230, v234, v233
	v_div_fmas_f32 v230, v230, v231, v234
	v_div_fixup_f32 v230, v230, v229, 1.0
	v_mul_f32_e32 v121, v121, v230
	v_lshlrev_b32_e32 v228, 16, v201
	v_mul_f32_e32 v228, 0xbfb8aa3b, v228
	v_exp_f32_e32 v229, v228
	s_nop 0
	v_add_f32_e32 v229, 1.0, v229
	s_nop 0
	v_div_scale_f32 v230, s[2:3], v229, v229, 1.0
	v_rcp_f32_e32 v231, v230
	s_nop 0
	v_fma_f32 v232, -v230, v231, 1.0
	v_fmac_f32_e32 v231, v232, v231
	v_div_scale_f32 v233, vcc, 1.0, v229, 1.0
	v_mul_f32_e32 v234, v233, v231
	v_fma_f32 v235, -v230, v234, v233
	v_fmac_f32_e32 v234, v235, v231
	v_fma_f32 v230, -v230, v234, v233
	v_div_fmas_f32 v230, v230, v231, v234
	v_div_fixup_f32 v230, v230, v229, 1.0
	v_mul_f32_e32 v122, v122, v230
	v_and_b32_e32 v228, 0xffff0000, v201
	v_mul_f32_e32 v228, 0xbfb8aa3b, v228
	v_exp_f32_e32 v229, v228
	s_nop 0
	v_add_f32_e32 v229, 1.0, v229
	s_nop 0
	v_div_scale_f32 v230, s[2:3], v229, v229, 1.0
	v_rcp_f32_e32 v231, v230
	s_nop 0
	v_fma_f32 v232, -v230, v231, 1.0
	v_fmac_f32_e32 v231, v232, v231
	v_div_scale_f32 v233, vcc, 1.0, v229, 1.0
	v_mul_f32_e32 v234, v233, v231
	v_fma_f32 v235, -v230, v234, v233
	v_fmac_f32_e32 v234, v235, v231
	v_fma_f32 v230, -v230, v234, v233
	v_div_fmas_f32 v230, v230, v231, v234
	v_div_fixup_f32 v230, v230, v229, 1.0
	v_mul_f32_e32 v123, v123, v230
	v_lshlrev_b32_e32 v228, 16, v202
	v_mul_f32_e32 v228, 0xbfb8aa3b, v228
	v_exp_f32_e32 v229, v228
	s_nop 0
	v_add_f32_e32 v229, 1.0, v229
	s_nop 0
	v_div_scale_f32 v230, s[2:3], v229, v229, 1.0
	v_rcp_f32_e32 v231, v230
	s_nop 0
	v_fma_f32 v232, -v230, v231, 1.0
	v_fmac_f32_e32 v231, v232, v231
	v_div_scale_f32 v233, vcc, 1.0, v229, 1.0
	v_mul_f32_e32 v234, v233, v231
	v_fma_f32 v235, -v230, v234, v233
	v_fmac_f32_e32 v234, v235, v231
	v_fma_f32 v230, -v230, v234, v233
	v_div_fmas_f32 v230, v230, v231, v234
	v_div_fixup_f32 v230, v230, v229, 1.0
	v_mul_f32_e32 v116, v116, v230
	v_and_b32_e32 v228, 0xffff0000, v202
	v_mul_f32_e32 v228, 0xbfb8aa3b, v228
	v_exp_f32_e32 v229, v228
	s_nop 0
	v_add_f32_e32 v229, 1.0, v229
	s_nop 0
	v_div_scale_f32 v230, s[2:3], v229, v229, 1.0
	v_rcp_f32_e32 v231, v230
	s_nop 0
	v_fma_f32 v232, -v230, v231, 1.0
	v_fmac_f32_e32 v231, v232, v231
	v_div_scale_f32 v233, vcc, 1.0, v229, 1.0
	v_mul_f32_e32 v234, v233, v231
	v_fma_f32 v235, -v230, v234, v233
	v_fmac_f32_e32 v234, v235, v231
	v_fma_f32 v230, -v230, v234, v233
	v_div_fmas_f32 v230, v230, v231, v234
	v_div_fixup_f32 v230, v230, v229, 1.0
	v_mul_f32_e32 v117, v117, v230
	v_lshlrev_b32_e32 v228, 16, v203
	v_mul_f32_e32 v228, 0xbfb8aa3b, v228
	v_exp_f32_e32 v229, v228
	s_nop 0
	v_add_f32_e32 v229, 1.0, v229
	s_nop 0
	v_div_scale_f32 v230, s[2:3], v229, v229, 1.0
	v_rcp_f32_e32 v231, v230
	s_nop 0
	v_fma_f32 v232, -v230, v231, 1.0
	v_fmac_f32_e32 v231, v232, v231
	v_div_scale_f32 v233, vcc, 1.0, v229, 1.0
	v_mul_f32_e32 v234, v233, v231
	v_fma_f32 v235, -v230, v234, v233
	v_fmac_f32_e32 v234, v235, v231
	v_fma_f32 v230, -v230, v234, v233
	v_div_fmas_f32 v230, v230, v231, v234
	v_div_fixup_f32 v230, v230, v229, 1.0
	v_mul_f32_e32 v118, v118, v230
	v_and_b32_e32 v228, 0xffff0000, v203
	v_mul_f32_e32 v228, 0xbfb8aa3b, v228
	v_exp_f32_e32 v229, v228
	s_nop 0
	v_add_f32_e32 v229, 1.0, v229
	s_nop 0
	v_div_scale_f32 v230, s[2:3], v229, v229, 1.0
	v_rcp_f32_e32 v231, v230
	s_nop 0
	v_fma_f32 v232, -v230, v231, 1.0
	v_fmac_f32_e32 v231, v232, v231
	v_div_scale_f32 v233, vcc, 1.0, v229, 1.0
	v_mul_f32_e32 v234, v233, v231
	v_fma_f32 v235, -v230, v234, v233
	v_fmac_f32_e32 v234, v235, v231
	v_fma_f32 v230, -v230, v234, v233
	v_div_fmas_f32 v230, v230, v231, v234
	v_div_fixup_f32 v230, v230, v229, 1.0
	v_mul_f32_e32 v119, v119, v230
	s_and_b64 vcc, exec, s[44:45]
	s_cbranch_vccz .Lmy_br_nopv_add_0_0_1
	v_lshlrev_b32_e32 v228, 16, v216
	v_add_f32_e32 v120, v120, v228
	v_and_b32_e32 v228, 0xffff0000, v216
	v_add_f32_e32 v121, v121, v228
	v_lshlrev_b32_e32 v228, 16, v217
	v_add_f32_e32 v122, v122, v228
	v_and_b32_e32 v228, 0xffff0000, v217
	v_add_f32_e32 v123, v123, v228
	v_lshlrev_b32_e32 v228, 16, v218
	v_add_f32_e32 v116, v116, v228
	v_and_b32_e32 v228, 0xffff0000, v218
	v_add_f32_e32 v117, v117, v228
	v_lshlrev_b32_e32 v228, 16, v219
	v_add_f32_e32 v118, v118, v228
	v_and_b32_e32 v228, 0xffff0000, v219
	v_add_f32_e32 v119, v119, v228
; __device__ __forceinline__ float b2f(u16 b) { return __uint_as_float(((uint32_t)b) << 16); }
; __device__ __forceinline__ float sigmoidf_(float x) { return 1.0f / (1.0f + __expf(-x)); }
; __device__ __forceinline__ void gemm_phase(const Ctx& cx, const GemmArgs& g_, char* shm) {
;     ...
;               const uint2 gv = *(const uint2*)(g.gate + (size_t)tok * NP + n0);
;               float v0 = sigmoidf_(b2f((u16)(gv.x & 0xffff))) * a[0], v1 = sigmoidf_(b2f((u16)(gv.x >> 16))) * a[1];
;               float v2 = sigmoidf_(b2f((u16)(gv.y & 0xffff))) * a[2], v3 = sigmoidf_(b2f((u16)(gv.y >> 16))) * a[3];
;               uint2* mp = (uint2*)(g.outb + (size_t)tok * DM + n0);
;               if (g.epi != EPI_BR0) {
;                 const uint2 pv = *mp;
;                 v0 += b2f((u16)(pv.x & 0xffff)); v1 += b2f((u16)(pv.x >> 16));
;                 v2 += b2f((u16)(pv.y & 0xffff)); v3 += b2f((u16)(pv.y >> 16));
;               }
;               uint2 o; o.x = pack2(v0, v1); o.y = pack2(v2, v3);
;               *mp = o;
.Lmy_br_nopv_add_0_0_1:
	v_cvt_pk_bf16_f32 v240, v120, v121
	v_cvt_pk_bf16_f32 v241, v122, v123
	v_cvt_pk_bf16_f32 v242, v116, v117
	v_cvt_pk_bf16_f32 v243, v118, v119
	s_nop 1
	v_permlane16_swap_b32_e32 v240, v242
	v_permlane16_swap_b32_e32 v241, v243
	v_mov_b32_e32 v244, v240
	v_mov_b32_e32 v245, v241
	v_mov_b32_e32 v246, v242
	v_mov_b32_e32 v247, v243
	v_mov_b32_dpp v240, v236 row_ror:8 row_mask:0xf bank_mask:0x3
	v_mov_b32_dpp v241, v237 row_ror:8 row_mask:0xf bank_mask:0x3
	v_mov_b32_dpp v242, v238 row_ror:8 row_mask:0xf bank_mask:0x3
	v_mov_b32_dpp v243, v239 row_ror:8 row_mask:0xf bank_mask:0x3
	v_mov_b32_dpp v236, v244 row_ror:8 row_mask:0xf bank_mask:0xc
	v_mov_b32_dpp v237, v245 row_ror:8 row_mask:0xf bank_mask:0xc
	v_mov_b32_dpp v238, v246 row_ror:8 row_mask:0xf bank_mask:0xc
	v_mov_b32_dpp v239, v247 row_ror:8 row_mask:0xf bank_mask:0xc
	global_store_dwordx4 v[188:189], v[236:239], off offset:32
	global_store_dwordx4 v[190:191], v[240:243], off offset:32
	s_nop 1
	v_lshlrev_b32_e32 v228, 16, v204
	v_mul_f32_e32 v228, 0xbfb8aa3b, v228
	v_exp_f32_e32 v229, v228
	s_nop 0
	v_add_f32_e32 v229, 1.0, v229
	s_nop 0
	v_div_scale_f32 v230, s[2:3], v229, v229, 1.0
	v_rcp_f32_e32 v231, v230
	s_nop 0
	v_fma_f32 v232, -v230, v231, 1.0
	v_fmac_f32_e32 v231, v232, v231
	v_div_scale_f32 v233, vcc, 1.0, v229, 1.0
	v_mul_f32_e32 v234, v233, v231
	v_fma_f32 v235, -v230, v234, v233
	v_fmac_f32_e32 v234, v235, v231
	v_fma_f32 v230, -v230, v234, v233
	v_div_fmas_f32 v230, v230, v231, v234
	v_div_fixup_f32 v230, v230, v229, 1.0
	v_mul_f32_e32 v112, v112, v230
	v_and_b32_e32 v228, 0xffff0000, v204
	v_mul_f32_e32 v228, 0xbfb8aa3b, v228
	v_exp_f32_e32 v229, v228
	s_nop 0
	v_add_f32_e32 v229, 1.0, v229
	s_nop 0
	v_div_scale_f32 v230, s[2:3], v229, v229, 1.0
	v_rcp_f32_e32 v231, v230
	s_nop 0
	v_fma_f32 v232, -v230, v231, 1.0
	v_fmac_f32_e32 v231, v232, v231
	v_div_scale_f32 v233, vcc, 1.0, v229, 1.0
	v_mul_f32_e32 v234, v233, v231
	v_fma_f32 v235, -v230, v234, v233
	v_fmac_f32_e32 v234, v235, v231
	v_fma_f32 v230, -v230, v234, v233
	v_div_fmas_f32 v230, v230, v231, v234
	v_div_fixup_f32 v230, v230, v229, 1.0
	v_mul_f32_e32 v113, v113, v230
	v_lshlrev_b32_e32 v228, 16, v205
	v_mul_f32_e32 v228, 0xbfb8aa3b, v228
	v_exp_f32_e32 v229, v228
	s_nop 0
	v_add_f32_e32 v229, 1.0, v229
	s_nop 0
	v_div_scale_f32 v230, s[2:3], v229, v229, 1.0
	v_rcp_f32_e32 v231, v230
	s_nop 0
	v_fma_f32 v232, -v230, v231, 1.0
	v_fmac_f32_e32 v231, v232, v231
	v_div_scale_f32 v233, vcc, 1.0, v229, 1.0
	v_mul_f32_e32 v234, v233, v231
	v_fma_f32 v235, -v230, v234, v233
	v_fmac_f32_e32 v234, v235, v231
	v_fma_f32 v230, -v230, v234, v233
	v_div_fmas_f32 v230, v230, v231, v234
	v_div_fixup_f32 v230, v230, v229, 1.0
	v_mul_f32_e32 v114, v114, v230
	v_and_b32_e32 v228, 0xffff0000, v205
	v_mul_f32_e32 v228, 0xbfb8aa3b, v228
	v_exp_f32_e32 v229, v228
	s_nop 0
	v_add_f32_e32 v229, 1.0, v229
	s_nop 0
	v_div_scale_f32 v230, s[2:3], v229, v229, 1.0
	v_rcp_f32_e32 v231, v230
	s_nop 0
	v_fma_f32 v232, -v230, v231, 1.0
	v_fmac_f32_e32 v231, v232, v231
	v_div_scale_f32 v233, vcc, 1.0, v229, 1.0
	v_mul_f32_e32 v234, v233, v231
	v_fma_f32 v235, -v230, v234, v233
	v_fmac_f32_e32 v234, v235, v231
	v_fma_f32 v230, -v230, v234, v233
	v_div_fmas_f32 v230, v230, v231, v234
	v_div_fixup_f32 v230, v230, v229, 1.0
	v_mul_f32_e32 v115, v115, v230
	v_lshlrev_b32_e32 v228, 16, v206
	v_mul_f32_e32 v228, 0xbfb8aa3b, v228
	v_exp_f32_e32 v229, v228
	s_nop 0
	v_add_f32_e32 v229, 1.0, v229
	s_nop 0
	v_div_scale_f32 v230, s[2:3], v229, v229, 1.0
	v_rcp_f32_e32 v231, v230
	s_nop 0
	v_fma_f32 v232, -v230, v231, 1.0
	v_fmac_f32_e32 v231, v232, v231
	v_div_scale_f32 v233, vcc, 1.0, v229, 1.0
	v_mul_f32_e32 v234, v233, v231
	v_fma_f32 v235, -v230, v234, v233
	v_fmac_f32_e32 v234, v235, v231
	v_fma_f32 v230, -v230, v234, v233
	v_div_fmas_f32 v230, v230, v231, v234
	v_div_fixup_f32 v230, v230, v229, 1.0
	v_mul_f32_e32 v108, v108, v230
	v_and_b32_e32 v228, 0xffff0000, v206
	v_mul_f32_e32 v228, 0xbfb8aa3b, v228
	v_exp_f32_e32 v229, v228
	s_nop 0
	v_add_f32_e32 v229, 1.0, v229
	s_nop 0
	v_div_scale_f32 v230, s[2:3], v229, v229, 1.0
	v_rcp_f32_e32 v231, v230
	s_nop 0
	v_fma_f32 v232, -v230, v231, 1.0
	v_fmac_f32_e32 v231, v232, v231
	v_div_scale_f32 v233, vcc, 1.0, v229, 1.0
	v_mul_f32_e32 v234, v233, v231
	v_fma_f32 v235, -v230, v234, v233
	v_fmac_f32_e32 v234, v235, v231
	v_fma_f32 v230, -v230, v234, v233
	v_div_fmas_f32 v230, v230, v231, v234
	v_div_fixup_f32 v230, v230, v229, 1.0
	v_mul_f32_e32 v109, v109, v230
	v_lshlrev_b32_e32 v228, 16, v207
	v_mul_f32_e32 v228, 0xbfb8aa3b, v228
	v_exp_f32_e32 v229, v228
	s_nop 0
	v_add_f32_e32 v229, 1.0, v229
	s_nop 0
	v_div_scale_f32 v230, s[2:3], v229, v229, 1.0
	v_rcp_f32_e32 v231, v230
	s_nop 0
	v_fma_f32 v232, -v230, v231, 1.0
	v_fmac_f32_e32 v231, v232, v231
	v_div_scale_f32 v233, vcc, 1.0, v229, 1.0
	v_mul_f32_e32 v234, v233, v231
	v_fma_f32 v235, -v230, v234, v233
	v_fmac_f32_e32 v234, v235, v231
	v_fma_f32 v230, -v230, v234, v233
	v_div_fmas_f32 v230, v230, v231, v234
	v_div_fixup_f32 v230, v230, v229, 1.0
	v_mul_f32_e32 v110, v110, v230
	v_and_b32_e32 v228, 0xffff0000, v207
	v_mul_f32_e32 v228, 0xbfb8aa3b, v228
	v_exp_f32_e32 v229, v228
	s_nop 0
	v_add_f32_e32 v229, 1.0, v229
	s_nop 0
	v_div_scale_f32 v230, s[2:3], v229, v229, 1.0
	v_rcp_f32_e32 v231, v230
	s_nop 0
	v_fma_f32 v232, -v230, v231, 1.0
	v_fmac_f32_e32 v231, v232, v231
	v_div_scale_f32 v233, vcc, 1.0, v229, 1.0
	v_mul_f32_e32 v234, v233, v231
	v_fma_f32 v235, -v230, v234, v233
	v_fmac_f32_e32 v234, v235, v231
	v_fma_f32 v230, -v230, v234, v233
	v_div_fmas_f32 v230, v230, v231, v234
	v_div_fixup_f32 v230, v230, v229, 1.0
	v_mul_f32_e32 v111, v111, v230
	s_and_b64 vcc, exec, s[44:45]
	s_cbranch_vccz .Lmy_br_nopv_add_0_1_0
	v_lshlrev_b32_e32 v228, 16, v220
	v_add_f32_e32 v112, v112, v228
	v_and_b32_e32 v228, 0xffff0000, v220
	v_add_f32_e32 v113, v113, v228
	v_lshlrev_b32_e32 v228, 16, v221
	v_add_f32_e32 v114, v114, v228
	v_and_b32_e32 v228, 0xffff0000, v221
	v_add_f32_e32 v115, v115, v228
	v_lshlrev_b32_e32 v228, 16, v222
	v_add_f32_e32 v108, v108, v228
	v_and_b32_e32 v228, 0xffff0000, v222
	v_add_f32_e32 v109, v109, v228
	v_lshlrev_b32_e32 v228, 16, v223
	v_add_f32_e32 v110, v110, v228
	v_and_b32_e32 v228, 0xffff0000, v223
	v_add_f32_e32 v111, v111, v228
; __device__ __forceinline__ float b2f(u16 b) { return __uint_as_float(((uint32_t)b) << 16); }
; __device__ __forceinline__ float sigmoidf_(float x) { return 1.0f / (1.0f + __expf(-x)); }
; __device__ __forceinline__ void gemm_phase(const Ctx& cx, const GemmArgs& g_, char* shm) {
;     ...
;               const uint2 gv = *(const uint2*)(g.gate + (size_t)tok * NP + n0);
;               float v0 = sigmoidf_(b2f((u16)(gv.x & 0xffff))) * a[0], v1 = sigmoidf_(b2f((u16)(gv.x >> 16))) * a[1];
;               float v2 = sigmoidf_(b2f((u16)(gv.y & 0xffff))) * a[2], v3 = sigmoidf_(b2f((u16)(gv.y >> 16))) * a[3];
;               uint2* mp = (uint2*)(g.outb + (size_t)tok * DM + n0);
;               if (g.epi != EPI_BR0) {
;                 const uint2 pv = *mp;
;                 v0 += b2f((u16)(pv.x & 0xffff)); v1 += b2f((u16)(pv.x >> 16));
;                 v2 += b2f((u16)(pv.y & 0xffff)); v3 += b2f((u16)(pv.y >> 16));
;               }
;               uint2 o; o.x = pack2(v0, v1); o.y = pack2(v2, v3);
;               *mp = o;
.Lmy_br_nopv_add_0_1_0:
	v_cvt_pk_bf16_f32 v236, v112, v113
	v_cvt_pk_bf16_f32 v237, v114, v115
	v_cvt_pk_bf16_f32 v238, v108, v109
	v_cvt_pk_bf16_f32 v239, v110, v111
	s_nop 1
	v_permlane16_swap_b32_e32 v236, v238
	v_permlane16_swap_b32_e32 v237, v239
	v_lshlrev_b32_e32 v228, 16, v208
	v_mul_f32_e32 v228, 0xbfb8aa3b, v228
	v_exp_f32_e32 v229, v228
	s_nop 0
	v_add_f32_e32 v229, 1.0, v229
	s_nop 0
	v_div_scale_f32 v230, s[2:3], v229, v229, 1.0
	v_rcp_f32_e32 v231, v230
	s_nop 0
	v_fma_f32 v232, -v230, v231, 1.0
	v_fmac_f32_e32 v231, v232, v231
	v_div_scale_f32 v233, vcc, 1.0, v229, 1.0
	v_mul_f32_e32 v234, v233, v231
	v_fma_f32 v235, -v230, v234, v233
	v_fmac_f32_e32 v234, v235, v231
	v_fma_f32 v230, -v230, v234, v233
	v_div_fmas_f32 v230, v230, v231, v234
	v_div_fixup_f32 v230, v230, v229, 1.0
	v_mul_f32_e32 v104, v104, v230
	v_and_b32_e32 v228, 0xffff0000, v208
	v_mul_f32_e32 v228, 0xbfb8aa3b, v228
	v_exp_f32_e32 v229, v228
	s_nop 0
	v_add_f32_e32 v229, 1.0, v229
	s_nop 0
	v_div_scale_f32 v230, s[2:3], v229, v229, 1.0
	v_rcp_f32_e32 v231, v230
	s_nop 0
	v_fma_f32 v232, -v230, v231, 1.0
	v_fmac_f32_e32 v231, v232, v231
	v_div_scale_f32 v233, vcc, 1.0, v229, 1.0
	v_mul_f32_e32 v234, v233, v231
	v_fma_f32 v235, -v230, v234, v233
	v_fmac_f32_e32 v234, v235, v231
	v_fma_f32 v230, -v230, v234, v233
	v_div_fmas_f32 v230, v230, v231, v234
	v_div_fixup_f32 v230, v230, v229, 1.0
	v_mul_f32_e32 v105, v105, v230
	v_lshlrev_b32_e32 v228, 16, v209
	v_mul_f32_e32 v228, 0xbfb8aa3b, v228
	v_exp_f32_e32 v229, v228
	s_nop 0
	v_add_f32_e32 v229, 1.0, v229
	s_nop 0
	v_div_scale_f32 v230, s[2:3], v229, v229, 1.0
	v_rcp_f32_e32 v231, v230
	s_nop 0
	v_fma_f32 v232, -v230, v231, 1.0
	v_fmac_f32_e32 v231, v232, v231
	v_div_scale_f32 v233, vcc, 1.0, v229, 1.0
	v_mul_f32_e32 v234, v233, v231
	v_fma_f32 v235, -v230, v234, v233
	v_fmac_f32_e32 v234, v235, v231
	v_fma_f32 v230, -v230, v234, v233
	v_div_fmas_f32 v230, v230, v231, v234
	v_div_fixup_f32 v230, v230, v229, 1.0
	v_mul_f32_e32 v106, v106, v230
	v_and_b32_e32 v228, 0xffff0000, v209
	v_mul_f32_e32 v228, 0xbfb8aa3b, v228
	v_exp_f32_e32 v229, v228
	s_nop 0
	v_add_f32_e32 v229, 1.0, v229
	s_nop 0
	v_div_scale_f32 v230, s[2:3], v229, v229, 1.0
	v_rcp_f32_e32 v231, v230
	s_nop 0
	v_fma_f32 v232, -v230, v231, 1.0
	v_fmac_f32_e32 v231, v232, v231
	v_div_scale_f32 v233, vcc, 1.0, v229, 1.0
	v_mul_f32_e32 v234, v233, v231
	v_fma_f32 v235, -v230, v234, v233
	v_fmac_f32_e32 v234, v235, v231
	v_fma_f32 v230, -v230, v234, v233
	v_div_fmas_f32 v230, v230, v231, v234
	v_div_fixup_f32 v230, v230, v229, 1.0
	v_mul_f32_e32 v107, v107, v230
	v_lshlrev_b32_e32 v228, 16, v210
	v_mul_f32_e32 v228, 0xbfb8aa3b, v228
	v_exp_f32_e32 v229, v228
	s_nop 0
	v_add_f32_e32 v229, 1.0, v229
	s_nop 0
	v_div_scale_f32 v230, s[2:3], v229, v229, 1.0
	v_rcp_f32_e32 v231, v230
	s_nop 0
	v_fma_f32 v232, -v230, v231, 1.0
	v_fmac_f32_e32 v231, v232, v231
	v_div_scale_f32 v233, vcc, 1.0, v229, 1.0
	v_mul_f32_e32 v234, v233, v231
	v_fma_f32 v235, -v230, v234, v233
	v_fmac_f32_e32 v234, v235, v231
	v_fma_f32 v230, -v230, v234, v233
	v_div_fmas_f32 v230, v230, v231, v234
	v_div_fixup_f32 v230, v230, v229, 1.0
	v_mul_f32_e32 v100, v100, v230
	v_and_b32_e32 v228, 0xffff0000, v210
	v_mul_f32_e32 v228, 0xbfb8aa3b, v228
	v_exp_f32_e32 v229, v228
	s_nop 0
	v_add_f32_e32 v229, 1.0, v229
	s_nop 0
	v_div_scale_f32 v230, s[2:3], v229, v229, 1.0
	v_rcp_f32_e32 v231, v230
	s_nop 0
	v_fma_f32 v232, -v230, v231, 1.0
	v_fmac_f32_e32 v231, v232, v231
	v_div_scale_f32 v233, vcc, 1.0, v229, 1.0
	v_mul_f32_e32 v234, v233, v231
	v_fma_f32 v235, -v230, v234, v233
	v_fmac_f32_e32 v234, v235, v231
	v_fma_f32 v230, -v230, v234, v233
	v_div_fmas_f32 v230, v230, v231, v234
	v_div_fixup_f32 v230, v230, v229, 1.0
	v_mul_f32_e32 v101, v101, v230
	v_lshlrev_b32_e32 v228, 16, v211
	v_mul_f32_e32 v228, 0xbfb8aa3b, v228
	v_exp_f32_e32 v229, v228
	s_nop 0
	v_add_f32_e32 v229, 1.0, v229
	s_nop 0
	v_div_scale_f32 v230, s[2:3], v229, v229, 1.0
	v_rcp_f32_e32 v231, v230
	s_nop 0
	v_fma_f32 v232, -v230, v231, 1.0
	v_fmac_f32_e32 v231, v232, v231
	v_div_scale_f32 v233, vcc, 1.0, v229, 1.0
	v_mul_f32_e32 v234, v233, v231
	v_fma_f32 v235, -v230, v234, v233
	v_fmac_f32_e32 v234, v235, v231
	v_fma_f32 v230, -v230, v234, v233
	v_div_fmas_f32 v230, v230, v231, v234
	v_div_fixup_f32 v230, v230, v229, 1.0
	v_mul_f32_e32 v102, v102, v230
	v_and_b32_e32 v228, 0xffff0000, v211
	v_mul_f32_e32 v228, 0xbfb8aa3b, v228
	v_exp_f32_e32 v229, v228
	s_nop 0
	v_add_f32_e32 v229, 1.0, v229
	s_nop 0
	v_div_scale_f32 v230, s[2:3], v229, v229, 1.0
	v_rcp_f32_e32 v231, v230
	s_nop 0
	v_fma_f32 v232, -v230, v231, 1.0
	v_fmac_f32_e32 v231, v232, v231
	v_div_scale_f32 v233, vcc, 1.0, v229, 1.0
	v_mul_f32_e32 v234, v233, v231
	v_fma_f32 v235, -v230, v234, v233
	v_fmac_f32_e32 v234, v235, v231
	v_fma_f32 v230, -v230, v234, v233
	v_div_fmas_f32 v230, v230, v231, v234
	v_div_fixup_f32 v230, v230, v229, 1.0
	v_mul_f32_e32 v103, v103, v230
	s_and_b64 vcc, exec, s[44:45]
	s_cbranch_vccz .Lmy_br_nopv_add_0_1_1
	v_lshlrev_b32_e32 v228, 16, v224
	v_add_f32_e32 v104, v104, v228
	v_and_b32_e32 v228, 0xffff0000, v224
	v_add_f32_e32 v105, v105, v228
	v_lshlrev_b32_e32 v228, 16, v225
	v_add_f32_e32 v106, v106, v228
	v_and_b32_e32 v228, 0xffff0000, v225
	v_add_f32_e32 v107, v107, v228
	v_lshlrev_b32_e32 v228, 16, v226
	v_add_f32_e32 v100, v100, v228
	v_and_b32_e32 v228, 0xffff0000, v226
	v_add_f32_e32 v101, v101, v228
	v_lshlrev_b32_e32 v228, 16, v227
	v_add_f32_e32 v102, v102, v228
	v_and_b32_e32 v228, 0xffff0000, v227
	v_add_f32_e32 v103, v103, v228
; __device__ __forceinline__ float b2f(u16 b) { return __uint_as_float(((uint32_t)b) << 16); }
; __device__ __forceinline__ float sigmoidf_(float x) { return 1.0f / (1.0f + __expf(-x)); }
; __device__ __forceinline__ void gemm_phase(const Ctx& cx, const GemmArgs& g_, char* shm) {
;     ...
;             } else {
;               const uint2 gv = *(const uint2*)(g.gate + (size_t)tok * NP + n0);
;               float v0 = sigmoidf_(b2f((u16)(gv.x & 0xffff))) * a[0], v1 = sigmoidf_(b2f((u16)(gv.x >> 16))) * a[1];
;               float v2 = sigmoidf_(b2f((u16)(gv.y & 0xffff))) * a[2], v3 = sigmoidf_(b2f((u16)(gv.y >> 16))) * a[3];
;               uint2* mp = (uint2*)(g.outb + (size_t)tok * DM + n0);
;               if (g.epi != EPI_BR0) {
;                 const uint2 pv = *mp;
;                 v0 += b2f((u16)(pv.x & 0xffff)); v1 += b2f((u16)(pv.x >> 16));
;                 v2 += b2f((u16)(pv.y & 0xffff)); v3 += b2f((u16)(pv.y >> 16));
;               }
;               uint2 o; o.x = pack2(v0, v1); o.y = pack2(v2, v3);
;               *mp = o;
;             }
.Lmy_br_nopv_add_0_1_1:
	v_cvt_pk_bf16_f32 v240, v104, v105
	v_cvt_pk_bf16_f32 v241, v106, v107
	v_cvt_pk_bf16_f32 v242, v100, v101
	v_cvt_pk_bf16_f32 v243, v102, v103
	s_nop 1
	v_permlane16_swap_b32_e32 v240, v242
	v_permlane16_swap_b32_e32 v241, v243
	v_mov_b32_e32 v244, v240
	v_mov_b32_e32 v245, v241
	v_mov_b32_e32 v246, v242
	v_mov_b32_e32 v247, v243
	v_mov_b32_dpp v240, v236 row_ror:8 row_mask:0xf bank_mask:0x3
	v_mov_b32_dpp v241, v237 row_ror:8 row_mask:0xf bank_mask:0x3
	v_mov_b32_dpp v242, v238 row_ror:8 row_mask:0xf bank_mask:0x3
	v_mov_b32_dpp v243, v239 row_ror:8 row_mask:0xf bank_mask:0x3
	v_mov_b32_dpp v236, v244 row_ror:8 row_mask:0xf bank_mask:0xc
	v_mov_b32_dpp v237, v245 row_ror:8 row_mask:0xf bank_mask:0xc
	v_mov_b32_dpp v238, v246 row_ror:8 row_mask:0xf bank_mask:0xc
	v_mov_b32_dpp v239, v247 row_ror:8 row_mask:0xf bank_mask:0xc
	global_store_dwordx4 v[188:189], v[236:239], off offset:288
	global_store_dwordx4 v[190:191], v[240:243], off offset:288
	s_nop 1
	v_lshl_add_u64 v[188:189], v[184:185], 0, s[8:9]
	v_lshl_add_u64 v[190:191], v[188:189], 0, s[6:7]
	v_add_u32_e32 v195, 16, v194
	v_mov_b64_e32 v[244:245], s[22:23]
	v_mad_i64_i32 v[244:245], s[4:5], v195, s76, v[244:245]
	v_lshl_add_u64 v[244:245], v[186:187], 1, v[244:245]
	global_load_dwordx2 v[196:197], v[244:245], off offset:0
	global_load_dwordx2 v[198:199], v[244:245], off offset:32
	global_load_dwordx2 v[200:201], v[244:245], off offset:64
	global_load_dwordx2 v[202:203], v[244:245], off offset:96
	global_load_dwordx2 v[204:205], v[244:245], off offset:256
	global_load_dwordx2 v[206:207], v[244:245], off offset:288
	global_load_dwordx2 v[208:209], v[244:245], off offset:320
	global_load_dwordx2 v[210:211], v[244:245], off offset:352
	s_and_b64 vcc, exec, s[44:45]
	s_cbranch_vccz .Lmy_br_nopv_ld_1
	v_mov_b32_e32 v192, v195
	v_ashrrev_i32_e32 v193, 31, v195
	v_lshlrev_b64 v[192:193], 12, v[192:193]
	v_lshl_add_u64 v[192:193], s[20:21], 0, v[192:193]
	v_lshl_add_u64 v[192:193], v[186:187], 1, v[192:193]
	global_load_dwordx2 v[212:213], v[192:193], off offset:0
	global_load_dwordx2 v[214:215], v[192:193], off offset:32
	global_load_dwordx2 v[216:217], v[192:193], off offset:64
	global_load_dwordx2 v[218:219], v[192:193], off offset:96
	global_load_dwordx2 v[220:221], v[192:193], off offset:256
	global_load_dwordx2 v[222:223], v[192:193], off offset:288
	global_load_dwordx2 v[224:225], v[192:193], off offset:320
	global_load_dwordx2 v[226:227], v[192:193], off offset:352
.Lmy_br_nopv_ld_1:
	s_waitcnt vmcnt(0)
	v_lshlrev_b32_e32 v228, 16, v196
	v_mul_f32_e32 v228, 0xbfb8aa3b, v228
	v_exp_f32_e32 v229, v228
	s_nop 0
	v_add_f32_e32 v229, 1.0, v229
	s_nop 0
	v_div_scale_f32 v230, s[2:3], v229, v229, 1.0
	v_rcp_f32_e32 v231, v230
	s_nop 0
	v_fma_f32 v232, -v230, v231, 1.0
	v_fmac_f32_e32 v231, v232, v231
	v_div_scale_f32 v233, vcc, 1.0, v229, 1.0
	v_mul_f32_e32 v234, v233, v231
	v_fma_f32 v235, -v230, v234, v233
	v_fmac_f32_e32 v234, v235, v231
	v_fma_f32 v230, -v230, v234, v233
	v_div_fmas_f32 v230, v230, v231, v234
	v_div_fixup_f32 v230, v230, v229, 1.0
	v_mul_f32_e32 v96, v96, v230
	v_and_b32_e32 v228, 0xffff0000, v196
	v_mul_f32_e32 v228, 0xbfb8aa3b, v228
	v_exp_f32_e32 v229, v228
	s_nop 0
	v_add_f32_e32 v229, 1.0, v229
	s_nop 0
	v_div_scale_f32 v230, s[2:3], v229, v229, 1.0
	v_rcp_f32_e32 v231, v230
	s_nop 0
	v_fma_f32 v232, -v230, v231, 1.0
	v_fmac_f32_e32 v231, v232, v231
	v_div_scale_f32 v233, vcc, 1.0, v229, 1.0
	v_mul_f32_e32 v234, v233, v231
	v_fma_f32 v235, -v230, v234, v233
	v_fmac_f32_e32 v234, v235, v231
	v_fma_f32 v230, -v230, v234, v233
	v_div_fmas_f32 v230, v230, v231, v234
	v_div_fixup_f32 v230, v230, v229, 1.0
	v_mul_f32_e32 v97, v97, v230
	v_lshlrev_b32_e32 v228, 16, v197
	v_mul_f32_e32 v228, 0xbfb8aa3b, v228
	v_exp_f32_e32 v229, v228
	s_nop 0
	v_add_f32_e32 v229, 1.0, v229
	s_nop 0
	v_div_scale_f32 v230, s[2:3], v229, v229, 1.0
	v_rcp_f32_e32 v231, v230
	s_nop 0
	v_fma_f32 v232, -v230, v231, 1.0
	v_fmac_f32_e32 v231, v232, v231
	v_div_scale_f32 v233, vcc, 1.0, v229, 1.0
	v_mul_f32_e32 v234, v233, v231
	v_fma_f32 v235, -v230, v234, v233
	v_fmac_f32_e32 v234, v235, v231
	v_fma_f32 v230, -v230, v234, v233
	v_div_fmas_f32 v230, v230, v231, v234
	v_div_fixup_f32 v230, v230, v229, 1.0
	v_mul_f32_e32 v98, v98, v230
	v_and_b32_e32 v228, 0xffff0000, v197
	v_mul_f32_e32 v228, 0xbfb8aa3b, v228
	v_exp_f32_e32 v229, v228
	s_nop 0
	v_add_f32_e32 v229, 1.0, v229
	s_nop 0
	v_div_scale_f32 v230, s[2:3], v229, v229, 1.0
	v_rcp_f32_e32 v231, v230
	s_nop 0
	v_fma_f32 v232, -v230, v231, 1.0
	v_fmac_f32_e32 v231, v232, v231
	v_div_scale_f32 v233, vcc, 1.0, v229, 1.0
	v_mul_f32_e32 v234, v233, v231
	v_fma_f32 v235, -v230, v234, v233
	v_fmac_f32_e32 v234, v235, v231
	v_fma_f32 v230, -v230, v234, v233
	v_div_fmas_f32 v230, v230, v231, v234
	v_div_fixup_f32 v230, v230, v229, 1.0
	v_mul_f32_e32 v99, v99, v230
	v_lshlrev_b32_e32 v228, 16, v198
	v_mul_f32_e32 v228, 0xbfb8aa3b, v228
	v_exp_f32_e32 v229, v228
	s_nop 0
	v_add_f32_e32 v229, 1.0, v229
	s_nop 0
	v_div_scale_f32 v230, s[2:3], v229, v229, 1.0
	v_rcp_f32_e32 v231, v230
	s_nop 0
	v_fma_f32 v232, -v230, v231, 1.0
	v_fmac_f32_e32 v231, v232, v231
	v_div_scale_f32 v233, vcc, 1.0, v229, 1.0
	v_mul_f32_e32 v234, v233, v231
	v_fma_f32 v235, -v230, v234, v233
	v_fmac_f32_e32 v234, v235, v231
	v_fma_f32 v230, -v230, v234, v233
	v_div_fmas_f32 v230, v230, v231, v234
	v_div_fixup_f32 v230, v230, v229, 1.0
	v_mul_f32_e32 v92, v92, v230
	v_and_b32_e32 v228, 0xffff0000, v198
	v_mul_f32_e32 v228, 0xbfb8aa3b, v228
	v_exp_f32_e32 v229, v228
	s_nop 0
	v_add_f32_e32 v229, 1.0, v229
	s_nop 0
	v_div_scale_f32 v230, s[2:3], v229, v229, 1.0
; __device__ __forceinline__ float b2f(u16 b) { return __uint_as_float(((uint32_t)b) << 16); }
; __device__ __forceinline__ float sigmoidf_(float x) { return 1.0f / (1.0f + __expf(-x)); }
; __device__ __forceinline__ void gemm_phase(const Ctx& cx, const GemmArgs& g_, char* shm) {
;     ...
;             } else {
;               const uint2 gv = *(const uint2*)(g.gate + (size_t)tok * NP + n0);
;               float v0 = sigmoidf_(b2f((u16)(gv.x & 0xffff))) * a[0], v1 = sigmoidf_(b2f((u16)(gv.x >> 16))) * a[1];
;               float v2 = sigmoidf_(b2f((u16)(gv.y & 0xffff))) * a[2], v3 = sigmoidf_(b2f((u16)(gv.y >> 16))) * a[3];
;               uint2* mp = (uint2*)(g.outb + (size_t)tok * DM + n0);
;               if (g.epi != EPI_BR0) {
;                 const uint2 pv = *mp;
;                 v0 += b2f((u16)(pv.x & 0xffff)); v1 += b2f((u16)(pv.x >> 16));
;                 v2 += b2f((u16)(pv.y & 0xffff)); v3 += b2f((u16)(pv.y >> 16));
;               }
;               uint2 o; o.x = pack2(v0, v1); o.y = pack2(v2, v3);
;               *mp = o;
;             }
	v_rcp_f32_e32 v231, v230
	s_nop 0
	v_fma_f32 v232, -v230, v231, 1.0
	v_fmac_f32_e32 v231, v232, v231
	v_div_scale_f32 v233, vcc, 1.0, v229, 1.0
	v_mul_f32_e32 v234, v233, v231
	v_fma_f32 v235, -v230, v234, v233
	v_fmac_f32_e32 v234, v235, v231
	v_fma_f32 v230, -v230, v234, v233
	v_div_fmas_f32 v230, v230, v231, v234
	v_div_fixup_f32 v230, v230, v229, 1.0
	v_mul_f32_e32 v93, v93, v230
	v_lshlrev_b32_e32 v228, 16, v199
	v_mul_f32_e32 v228, 0xbfb8aa3b, v228
	v_exp_f32_e32 v229, v228
	s_nop 0
	v_add_f32_e32 v229, 1.0, v229
	s_nop 0
	v_div_scale_f32 v230, s[2:3], v229, v229, 1.0
	v_rcp_f32_e32 v231, v230
	s_nop 0
	v_fma_f32 v232, -v230, v231, 1.0
	v_fmac_f32_e32 v231, v232, v231
	v_div_scale_f32 v233, vcc, 1.0, v229, 1.0
	v_mul_f32_e32 v234, v233, v231
	v_fma_f32 v235, -v230, v234, v233
	v_fmac_f32_e32 v234, v235, v231
	v_fma_f32 v230, -v230, v234, v233
	v_div_fmas_f32 v230, v230, v231, v234
	v_div_fixup_f32 v230, v230, v229, 1.0
	v_mul_f32_e32 v94, v94, v230
	v_and_b32_e32 v228, 0xffff0000, v199
	v_mul_f32_e32 v228, 0xbfb8aa3b, v228
	v_exp_f32_e32 v229, v228
	s_nop 0
	v_add_f32_e32 v229, 1.0, v229
	s_nop 0
	v_div_scale_f32 v230, s[2:3], v229, v229, 1.0
	v_rcp_f32_e32 v231, v230
	s_nop 0
	v_fma_f32 v232, -v230, v231, 1.0
	v_fmac_f32_e32 v231, v232, v231
	v_div_scale_f32 v233, vcc, 1.0, v229, 1.0
	v_mul_f32_e32 v234, v233, v231
	v_fma_f32 v235, -v230, v234, v233
	v_fmac_f32_e32 v234, v235, v231
	v_fma_f32 v230, -v230, v234, v233
	v_div_fmas_f32 v230, v230, v231, v234
	v_div_fixup_f32 v230, v230, v229, 1.0
	v_mul_f32_e32 v95, v95, v230
	s_and_b64 vcc, exec, s[44:45]
	s_cbranch_vccz .Lmy_br_nopv_add_1_0_0
	v_lshlrev_b32_e32 v228, 16, v212
	v_add_f32_e32 v96, v96, v228
	v_and_b32_e32 v228, 0xffff0000, v212
	v_add_f32_e32 v97, v97, v228
	v_lshlrev_b32_e32 v228, 16, v213
	v_add_f32_e32 v98, v98, v228
	v_and_b32_e32 v228, 0xffff0000, v213
	v_add_f32_e32 v99, v99, v228
	v_lshlrev_b32_e32 v228, 16, v214
	v_add_f32_e32 v92, v92, v228
	v_and_b32_e32 v228, 0xffff0000, v214
	v_add_f32_e32 v93, v93, v228
	v_lshlrev_b32_e32 v228, 16, v215
	v_add_f32_e32 v94, v94, v228
	v_and_b32_e32 v228, 0xffff0000, v215
	v_add_f32_e32 v95, v95, v228
.Lmy_br_nopv_add_1_0_0:
	v_cvt_pk_bf16_f32 v236, v96, v97
	v_cvt_pk_bf16_f32 v237, v98, v99
	v_cvt_pk_bf16_f32 v238, v92, v93
	v_cvt_pk_bf16_f32 v239, v94, v95
	s_nop 1
	v_permlane16_swap_b32_e32 v236, v238
	v_permlane16_swap_b32_e32 v237, v239
	v_lshlrev_b32_e32 v228, 16, v200
	v_mul_f32_e32 v228, 0xbfb8aa3b, v228
	v_exp_f32_e32 v229, v228
	s_nop 0
	v_add_f32_e32 v229, 1.0, v229
	s_nop 0
	v_div_scale_f32 v230, s[2:3], v229, v229, 1.0
	v_rcp_f32_e32 v231, v230
	s_nop 0
	v_fma_f32 v232, -v230, v231, 1.0
	v_fmac_f32_e32 v231, v232, v231
	v_div_scale_f32 v233, vcc, 1.0, v229, 1.0
	v_mul_f32_e32 v234, v233, v231
	v_fma_f32 v235, -v230, v234, v233
	v_fmac_f32_e32 v234, v235, v231
	v_fma_f32 v230, -v230, v234, v233
	v_div_fmas_f32 v230, v230, v231, v234
	v_div_fixup_f32 v230, v230, v229, 1.0
	v_mul_f32_e32 v88, v88, v230
	v_and_b32_e32 v228, 0xffff0000, v200
	v_mul_f32_e32 v228, 0xbfb8aa3b, v228
	v_exp_f32_e32 v229, v228
	s_nop 0
	v_add_f32_e32 v229, 1.0, v229
	s_nop 0
	v_div_scale_f32 v230, s[2:3], v229, v229, 1.0
	v_rcp_f32_e32 v231, v230
	s_nop 0
	v_fma_f32 v232, -v230, v231, 1.0
	v_fmac_f32_e32 v231, v232, v231
	v_div_scale_f32 v233, vcc, 1.0, v229, 1.0
	v_mul_f32_e32 v234, v233, v231
	v_fma_f32 v235, -v230, v234, v233
	v_fmac_f32_e32 v234, v235, v231
	v_fma_f32 v230, -v230, v234, v233
	v_div_fmas_f32 v230, v230, v231, v234
	v_div_fixup_f32 v230, v230, v229, 1.0
	v_mul_f32_e32 v89, v89, v230
	v_lshlrev_b32_e32 v228, 16, v201
	v_mul_f32_e32 v228, 0xbfb8aa3b, v228
	v_exp_f32_e32 v229, v228
	s_nop 0
	v_add_f32_e32 v229, 1.0, v229
	s_nop 0
	v_div_scale_f32 v230, s[2:3], v229, v229, 1.0
	v_rcp_f32_e32 v231, v230
	s_nop 0
	v_fma_f32 v232, -v230, v231, 1.0
	v_fmac_f32_e32 v231, v232, v231
	v_div_scale_f32 v233, vcc, 1.0, v229, 1.0
	v_mul_f32_e32 v234, v233, v231
	v_fma_f32 v235, -v230, v234, v233
	v_fmac_f32_e32 v234, v235, v231
	v_fma_f32 v230, -v230, v234, v233
	v_div_fmas_f32 v230, v230, v231, v234
	v_div_fixup_f32 v230, v230, v229, 1.0
	v_mul_f32_e32 v90, v90, v230
	v_and_b32_e32 v228, 0xffff0000, v201
	v_mul_f32_e32 v228, 0xbfb8aa3b, v228
	v_exp_f32_e32 v229, v228
	s_nop 0
	v_add_f32_e32 v229, 1.0, v229
	s_nop 0
	v_div_scale_f32 v230, s[2:3], v229, v229, 1.0
	v_rcp_f32_e32 v231, v230
	s_nop 0
	v_fma_f32 v232, -v230, v231, 1.0
	v_fmac_f32_e32 v231, v232, v231
	v_div_scale_f32 v233, vcc, 1.0, v229, 1.0
	v_mul_f32_e32 v234, v233, v231
	v_fma_f32 v235, -v230, v234, v233
	v_fmac_f32_e32 v234, v235, v231
	v_fma_f32 v230, -v230, v234, v233
	v_div_fmas_f32 v230, v230, v231, v234
	v_div_fixup_f32 v230, v230, v229, 1.0
	v_mul_f32_e32 v91, v91, v230
	v_lshlrev_b32_e32 v228, 16, v202
	v_mul_f32_e32 v228, 0xbfb8aa3b, v228
	v_exp_f32_e32 v229, v228
	s_nop 0
	v_add_f32_e32 v229, 1.0, v229
	s_nop 0
	v_div_scale_f32 v230, s[2:3], v229, v229, 1.0
	v_rcp_f32_e32 v231, v230
	s_nop 0
	v_fma_f32 v232, -v230, v231, 1.0
	v_fmac_f32_e32 v231, v232, v231
	v_div_scale_f32 v233, vcc, 1.0, v229, 1.0
	v_mul_f32_e32 v234, v233, v231
	v_fma_f32 v235, -v230, v234, v233
	v_fmac_f32_e32 v234, v235, v231
	v_fma_f32 v230, -v230, v234, v233
	v_div_fmas_f32 v230, v230, v231, v234
	v_div_fixup_f32 v230, v230, v229, 1.0
	v_mul_f32_e32 v84, v84, v230
	v_and_b32_e32 v228, 0xffff0000, v202
	v_mul_f32_e32 v228, 0xbfb8aa3b, v228
	v_exp_f32_e32 v229, v228
	s_nop 0
	v_add_f32_e32 v229, 1.0, v229
	s_nop 0
	v_div_scale_f32 v230, s[2:3], v229, v229, 1.0
	v_rcp_f32_e32 v231, v230
	s_nop 0
	v_fma_f32 v232, -v230, v231, 1.0
	v_fmac_f32_e32 v231, v232, v231
	v_div_scale_f32 v233, vcc, 1.0, v229, 1.0
; __device__ __forceinline__ float b2f(u16 b) { return __uint_as_float(((uint32_t)b) << 16); }
; __device__ __forceinline__ float sigmoidf_(float x) { return 1.0f / (1.0f + __expf(-x)); }
; __device__ __forceinline__ void gemm_phase(const Ctx& cx, const GemmArgs& g_, char* shm) {
;     ...
;             } else {
;               const uint2 gv = *(const uint2*)(g.gate + (size_t)tok * NP + n0);
;               float v0 = sigmoidf_(b2f((u16)(gv.x & 0xffff))) * a[0], v1 = sigmoidf_(b2f((u16)(gv.x >> 16))) * a[1];
;               float v2 = sigmoidf_(b2f((u16)(gv.y & 0xffff))) * a[2], v3 = sigmoidf_(b2f((u16)(gv.y >> 16))) * a[3];
;               uint2* mp = (uint2*)(g.outb + (size_t)tok * DM + n0);
;               if (g.epi != EPI_BR0) {
;                 const uint2 pv = *mp;
;                 v0 += b2f((u16)(pv.x & 0xffff)); v1 += b2f((u16)(pv.x >> 16));
;                 v2 += b2f((u16)(pv.y & 0xffff)); v3 += b2f((u16)(pv.y >> 16));
;               }
;               uint2 o; o.x = pack2(v0, v1); o.y = pack2(v2, v3);
;               *mp = o;
;             }
	v_mul_f32_e32 v234, v233, v231
	v_fma_f32 v235, -v230, v234, v233
	v_fmac_f32_e32 v234, v235, v231
	v_fma_f32 v230, -v230, v234, v233
	v_div_fmas_f32 v230, v230, v231, v234
	v_div_fixup_f32 v230, v230, v229, 1.0
	v_mul_f32_e32 v85, v85, v230
	v_lshlrev_b32_e32 v228, 16, v203
	v_mul_f32_e32 v228, 0xbfb8aa3b, v228
	v_exp_f32_e32 v229, v228
	s_nop 0
	v_add_f32_e32 v229, 1.0, v229
	s_nop 0
	v_div_scale_f32 v230, s[2:3], v229, v229, 1.0
	v_rcp_f32_e32 v231, v230
	s_nop 0
	v_fma_f32 v232, -v230, v231, 1.0
	v_fmac_f32_e32 v231, v232, v231
	v_div_scale_f32 v233, vcc, 1.0, v229, 1.0
	v_mul_f32_e32 v234, v233, v231
	v_fma_f32 v235, -v230, v234, v233
	v_fmac_f32_e32 v234, v235, v231
	v_fma_f32 v230, -v230, v234, v233
	v_div_fmas_f32 v230, v230, v231, v234
	v_div_fixup_f32 v230, v230, v229, 1.0
	v_mul_f32_e32 v86, v86, v230
	v_and_b32_e32 v228, 0xffff0000, v203
	v_mul_f32_e32 v228, 0xbfb8aa3b, v228
	v_exp_f32_e32 v229, v228
	s_nop 0
	v_add_f32_e32 v229, 1.0, v229
	s_nop 0
	v_div_scale_f32 v230, s[2:3], v229, v229, 1.0
	v_rcp_f32_e32 v231, v230
	s_nop 0
	v_fma_f32 v232, -v230, v231, 1.0
	v_fmac_f32_e32 v231, v232, v231
	v_div_scale_f32 v233, vcc, 1.0, v229, 1.0
	v_mul_f32_e32 v234, v233, v231
	v_fma_f32 v235, -v230, v234, v233
	v_fmac_f32_e32 v234, v235, v231
	v_fma_f32 v230, -v230, v234, v233
	v_div_fmas_f32 v230, v230, v231, v234
	v_div_fixup_f32 v230, v230, v229, 1.0
	v_mul_f32_e32 v87, v87, v230
	s_and_b64 vcc, exec, s[44:45]
	s_cbranch_vccz .Lmy_br_nopv_add_1_0_1
	v_lshlrev_b32_e32 v228, 16, v216
	v_add_f32_e32 v88, v88, v228
	v_and_b32_e32 v228, 0xffff0000, v216
	v_add_f32_e32 v89, v89, v228
	v_lshlrev_b32_e32 v228, 16, v217
	v_add_f32_e32 v90, v90, v228
	v_and_b32_e32 v228, 0xffff0000, v217
	v_add_f32_e32 v91, v91, v228
	v_lshlrev_b32_e32 v228, 16, v218
	v_add_f32_e32 v84, v84, v228
	v_and_b32_e32 v228, 0xffff0000, v218
	v_add_f32_e32 v85, v85, v228
	v_lshlrev_b32_e32 v228, 16, v219
	v_add_f32_e32 v86, v86, v228
	v_and_b32_e32 v228, 0xffff0000, v219
	v_add_f32_e32 v87, v87, v228
.Lmy_br_nopv_add_1_0_1:
	v_cvt_pk_bf16_f32 v240, v88, v89
	v_cvt_pk_bf16_f32 v241, v90, v91
	v_cvt_pk_bf16_f32 v242, v84, v85
	v_cvt_pk_bf16_f32 v243, v86, v87
	s_nop 1
	v_permlane16_swap_b32_e32 v240, v242
	v_permlane16_swap_b32_e32 v241, v243
	v_mov_b32_e32 v244, v240
	v_mov_b32_e32 v245, v241
	v_mov_b32_e32 v246, v242
	v_mov_b32_e32 v247, v243
	v_mov_b32_dpp v240, v236 row_ror:8 row_mask:0xf bank_mask:0x3
	v_mov_b32_dpp v241, v237 row_ror:8 row_mask:0xf bank_mask:0x3
	v_mov_b32_dpp v242, v238 row_ror:8 row_mask:0xf bank_mask:0x3
	v_mov_b32_dpp v243, v239 row_ror:8 row_mask:0xf bank_mask:0x3
	v_mov_b32_dpp v236, v244 row_ror:8 row_mask:0xf bank_mask:0xc
	v_mov_b32_dpp v237, v245 row_ror:8 row_mask:0xf bank_mask:0xc
	v_mov_b32_dpp v238, v246 row_ror:8 row_mask:0xf bank_mask:0xc
	v_mov_b32_dpp v239, v247 row_ror:8 row_mask:0xf bank_mask:0xc
	global_store_dwordx4 v[188:189], v[236:239], off offset:32
	global_store_dwordx4 v[190:191], v[240:243], off offset:32
	s_nop 1
	v_lshlrev_b32_e32 v228, 16, v204
	v_mul_f32_e32 v228, 0xbfb8aa3b, v228
	v_exp_f32_e32 v229, v228
	s_nop 0
	v_add_f32_e32 v229, 1.0, v229
	s_nop 0
	v_div_scale_f32 v230, s[2:3], v229, v229, 1.0
	v_rcp_f32_e32 v231, v230
	s_nop 0
	v_fma_f32 v232, -v230, v231, 1.0
	v_fmac_f32_e32 v231, v232, v231
	v_div_scale_f32 v233, vcc, 1.0, v229, 1.0
	v_mul_f32_e32 v234, v233, v231
	v_fma_f32 v235, -v230, v234, v233
	v_fmac_f32_e32 v234, v235, v231
	v_fma_f32 v230, -v230, v234, v233
	v_div_fmas_f32 v230, v230, v231, v234
	v_div_fixup_f32 v230, v230, v229, 1.0
	v_mul_f32_e32 v80, v80, v230
	v_and_b32_e32 v228, 0xffff0000, v204
	v_mul_f32_e32 v228, 0xbfb8aa3b, v228
	v_exp_f32_e32 v229, v228
	s_nop 0
	v_add_f32_e32 v229, 1.0, v229
	s_nop 0
	v_div_scale_f32 v230, s[2:3], v229, v229, 1.0
	v_rcp_f32_e32 v231, v230
	s_nop 0
	v_fma_f32 v232, -v230, v231, 1.0
	v_fmac_f32_e32 v231, v232, v231
	v_div_scale_f32 v233, vcc, 1.0, v229, 1.0
	v_mul_f32_e32 v234, v233, v231
	v_fma_f32 v235, -v230, v234, v233
	v_fmac_f32_e32 v234, v235, v231
	v_fma_f32 v230, -v230, v234, v233
	v_div_fmas_f32 v230, v230, v231, v234
	v_div_fixup_f32 v230, v230, v229, 1.0
	v_mul_f32_e32 v81, v81, v230
	v_lshlrev_b32_e32 v228, 16, v205
	v_mul_f32_e32 v228, 0xbfb8aa3b, v228
	v_exp_f32_e32 v229, v228
	s_nop 0
	v_add_f32_e32 v229, 1.0, v229
	s_nop 0
	v_div_scale_f32 v230, s[2:3], v229, v229, 1.0
	v_rcp_f32_e32 v231, v230
	s_nop 0
	v_fma_f32 v232, -v230, v231, 1.0
	v_fmac_f32_e32 v231, v232, v231
	v_div_scale_f32 v233, vcc, 1.0, v229, 1.0
	v_mul_f32_e32 v234, v233, v231
	v_fma_f32 v235, -v230, v234, v233
	v_fmac_f32_e32 v234, v235, v231
	v_fma_f32 v230, -v230, v234, v233
	v_div_fmas_f32 v230, v230, v231, v234
	v_div_fixup_f32 v230, v230, v229, 1.0
	v_mul_f32_e32 v82, v82, v230
	v_and_b32_e32 v228, 0xffff0000, v205
	v_mul_f32_e32 v228, 0xbfb8aa3b, v228
	v_exp_f32_e32 v229, v228
	s_nop 0
	v_add_f32_e32 v229, 1.0, v229
	s_nop 0
	v_div_scale_f32 v230, s[2:3], v229, v229, 1.0
	v_rcp_f32_e32 v231, v230
	s_nop 0
	v_fma_f32 v232, -v230, v231, 1.0
	v_fmac_f32_e32 v231, v232, v231
	v_div_scale_f32 v233, vcc, 1.0, v229, 1.0
	v_mul_f32_e32 v234, v233, v231
	v_fma_f32 v235, -v230, v234, v233
	v_fmac_f32_e32 v234, v235, v231
	v_fma_f32 v230, -v230, v234, v233
	v_div_fmas_f32 v230, v230, v231, v234
	v_div_fixup_f32 v230, v230, v229, 1.0
	v_mul_f32_e32 v83, v83, v230
	v_lshlrev_b32_e32 v228, 16, v206
	v_mul_f32_e32 v228, 0xbfb8aa3b, v228
	v_exp_f32_e32 v229, v228
	s_nop 0
	v_add_f32_e32 v229, 1.0, v229
	s_nop 0
	v_div_scale_f32 v230, s[2:3], v229, v229, 1.0
	v_rcp_f32_e32 v231, v230
	s_nop 0
	v_fma_f32 v232, -v230, v231, 1.0
	v_fmac_f32_e32 v231, v232, v231
; __device__ __forceinline__ float b2f(u16 b) { return __uint_as_float(((uint32_t)b) << 16); }
; __device__ __forceinline__ float sigmoidf_(float x) { return 1.0f / (1.0f + __expf(-x)); }
; __device__ __forceinline__ void gemm_phase(const Ctx& cx, const GemmArgs& g_, char* shm) {
;     ...
;             } else {
;               const uint2 gv = *(const uint2*)(g.gate + (size_t)tok * NP + n0);
;               float v0 = sigmoidf_(b2f((u16)(gv.x & 0xffff))) * a[0], v1 = sigmoidf_(b2f((u16)(gv.x >> 16))) * a[1];
;               float v2 = sigmoidf_(b2f((u16)(gv.y & 0xffff))) * a[2], v3 = sigmoidf_(b2f((u16)(gv.y >> 16))) * a[3];
;               uint2* mp = (uint2*)(g.outb + (size_t)tok * DM + n0);
;               if (g.epi != EPI_BR0) {
;                 const uint2 pv = *mp;
;                 v0 += b2f((u16)(pv.x & 0xffff)); v1 += b2f((u16)(pv.x >> 16));
;                 v2 += b2f((u16)(pv.y & 0xffff)); v3 += b2f((u16)(pv.y >> 16));
;               }
;               uint2 o; o.x = pack2(v0, v1); o.y = pack2(v2, v3);
;               *mp = o;
;             }
	v_div_scale_f32 v233, vcc, 1.0, v229, 1.0
	v_mul_f32_e32 v234, v233, v231
	v_fma_f32 v235, -v230, v234, v233
	v_fmac_f32_e32 v234, v235, v231
	v_fma_f32 v230, -v230, v234, v233
	v_div_fmas_f32 v230, v230, v231, v234
	v_div_fixup_f32 v230, v230, v229, 1.0
	v_mul_f32_e32 v76, v76, v230
	v_and_b32_e32 v228, 0xffff0000, v206
	v_mul_f32_e32 v228, 0xbfb8aa3b, v228
	v_exp_f32_e32 v229, v228
	s_nop 0
	v_add_f32_e32 v229, 1.0, v229
	s_nop 0
	v_div_scale_f32 v230, s[2:3], v229, v229, 1.0
	v_rcp_f32_e32 v231, v230
	s_nop 0
	v_fma_f32 v232, -v230, v231, 1.0
	v_fmac_f32_e32 v231, v232, v231
	v_div_scale_f32 v233, vcc, 1.0, v229, 1.0
	v_mul_f32_e32 v234, v233, v231
	v_fma_f32 v235, -v230, v234, v233
	v_fmac_f32_e32 v234, v235, v231
	v_fma_f32 v230, -v230, v234, v233
	v_div_fmas_f32 v230, v230, v231, v234
	v_div_fixup_f32 v230, v230, v229, 1.0
	v_mul_f32_e32 v77, v77, v230
	v_lshlrev_b32_e32 v228, 16, v207
	v_mul_f32_e32 v228, 0xbfb8aa3b, v228
	v_exp_f32_e32 v229, v228
	s_nop 0
	v_add_f32_e32 v229, 1.0, v229
	s_nop 0
	v_div_scale_f32 v230, s[2:3], v229, v229, 1.0
	v_rcp_f32_e32 v231, v230
	s_nop 0
	v_fma_f32 v232, -v230, v231, 1.0
	v_fmac_f32_e32 v231, v232, v231
	v_div_scale_f32 v233, vcc, 1.0, v229, 1.0
	v_mul_f32_e32 v234, v233, v231
	v_fma_f32 v235, -v230, v234, v233
	v_fmac_f32_e32 v234, v235, v231
	v_fma_f32 v230, -v230, v234, v233
	v_div_fmas_f32 v230, v230, v231, v234
	v_div_fixup_f32 v230, v230, v229, 1.0
	v_mul_f32_e32 v78, v78, v230
	v_and_b32_e32 v228, 0xffff0000, v207
	v_mul_f32_e32 v228, 0xbfb8aa3b, v228
	v_exp_f32_e32 v229, v228
	s_nop 0
	v_add_f32_e32 v229, 1.0, v229
	s_nop 0
	v_div_scale_f32 v230, s[2:3], v229, v229, 1.0
	v_rcp_f32_e32 v231, v230
	s_nop 0
	v_fma_f32 v232, -v230, v231, 1.0
	v_fmac_f32_e32 v231, v232, v231
	v_div_scale_f32 v233, vcc, 1.0, v229, 1.0
	v_mul_f32_e32 v234, v233, v231
	v_fma_f32 v235, -v230, v234, v233
	v_fmac_f32_e32 v234, v235, v231
	v_fma_f32 v230, -v230, v234, v233
	v_div_fmas_f32 v230, v230, v231, v234
	v_div_fixup_f32 v230, v230, v229, 1.0
	v_mul_f32_e32 v79, v79, v230
	s_and_b64 vcc, exec, s[44:45]
	s_cbranch_vccz .Lmy_br_nopv_add_1_1_0
	v_lshlrev_b32_e32 v228, 16, v220
	v_add_f32_e32 v80, v80, v228
	v_and_b32_e32 v228, 0xffff0000, v220
	v_add_f32_e32 v81, v81, v228
	v_lshlrev_b32_e32 v228, 16, v221
	v_add_f32_e32 v82, v82, v228
	v_and_b32_e32 v228, 0xffff0000, v221
	v_add_f32_e32 v83, v83, v228
	v_lshlrev_b32_e32 v228, 16, v222
	v_add_f32_e32 v76, v76, v228
	v_and_b32_e32 v228, 0xffff0000, v222
	v_add_f32_e32 v77, v77, v228
	v_lshlrev_b32_e32 v228, 16, v223
	v_add_f32_e32 v78, v78, v228
	v_and_b32_e32 v228, 0xffff0000, v223
	v_add_f32_e32 v79, v79, v228
.Lmy_br_nopv_add_1_1_0:
	v_cvt_pk_bf16_f32 v236, v80, v81
	v_cvt_pk_bf16_f32 v237, v82, v83
	v_cvt_pk_bf16_f32 v238, v76, v77
	v_cvt_pk_bf16_f32 v239, v78, v79
	s_nop 1
	v_permlane16_swap_b32_e32 v236, v238
	v_permlane16_swap_b32_e32 v237, v239
	v_lshlrev_b32_e32 v228, 16, v208
	v_mul_f32_e32 v228, 0xbfb8aa3b, v228
	v_exp_f32_e32 v229, v228
	s_nop 0
	v_add_f32_e32 v229, 1.0, v229
	s_nop 0
	v_div_scale_f32 v230, s[2:3], v229, v229, 1.0
	v_rcp_f32_e32 v231, v230
	s_nop 0
	v_fma_f32 v232, -v230, v231, 1.0
	v_fmac_f32_e32 v231, v232, v231
	v_div_scale_f32 v233, vcc, 1.0, v229, 1.0
	v_mul_f32_e32 v234, v233, v231
	v_fma_f32 v235, -v230, v234, v233
	v_fmac_f32_e32 v234, v235, v231
	v_fma_f32 v230, -v230, v234, v233
	v_div_fmas_f32 v230, v230, v231, v234
	v_div_fixup_f32 v230, v230, v229, 1.0
	v_mul_f32_e32 v72, v72, v230
	v_and_b32_e32 v228, 0xffff0000, v208
	v_mul_f32_e32 v228, 0xbfb8aa3b, v228
	v_exp_f32_e32 v229, v228
	s_nop 0
	v_add_f32_e32 v229, 1.0, v229
	s_nop 0
	v_div_scale_f32 v230, s[2:3], v229, v229, 1.0
	v_rcp_f32_e32 v231, v230
	s_nop 0
	v_fma_f32 v232, -v230, v231, 1.0
	v_fmac_f32_e32 v231, v232, v231
	v_div_scale_f32 v233, vcc, 1.0, v229, 1.0
	v_mul_f32_e32 v234, v233, v231
	v_fma_f32 v235, -v230, v234, v233
	v_fmac_f32_e32 v234, v235, v231
	v_fma_f32 v230, -v230, v234, v233
	v_div_fmas_f32 v230, v230, v231, v234
	v_div_fixup_f32 v230, v230, v229, 1.0
	v_mul_f32_e32 v73, v73, v230
	v_lshlrev_b32_e32 v228, 16, v209
	v_mul_f32_e32 v228, 0xbfb8aa3b, v228
	v_exp_f32_e32 v229, v228
	s_nop 0
	v_add_f32_e32 v229, 1.0, v229
	s_nop 0
	v_div_scale_f32 v230, s[2:3], v229, v229, 1.0
	v_rcp_f32_e32 v231, v230
	s_nop 0
	v_fma_f32 v232, -v230, v231, 1.0
	v_fmac_f32_e32 v231, v232, v231
	v_div_scale_f32 v233, vcc, 1.0, v229, 1.0
	v_mul_f32_e32 v234, v233, v231
	v_fma_f32 v235, -v230, v234, v233
	v_fmac_f32_e32 v234, v235, v231
	v_fma_f32 v230, -v230, v234, v233
	v_div_fmas_f32 v230, v230, v231, v234
	v_div_fixup_f32 v230, v230, v229, 1.0
	v_mul_f32_e32 v74, v74, v230
	v_and_b32_e32 v228, 0xffff0000, v209
	v_mul_f32_e32 v228, 0xbfb8aa3b, v228
	v_exp_f32_e32 v229, v228
	s_nop 0
	v_add_f32_e32 v229, 1.0, v229
	s_nop 0
	v_div_scale_f32 v230, s[2:3], v229, v229, 1.0
	v_rcp_f32_e32 v231, v230
	s_nop 0
	v_fma_f32 v232, -v230, v231, 1.0
	v_fmac_f32_e32 v231, v232, v231
	v_div_scale_f32 v233, vcc, 1.0, v229, 1.0
	v_mul_f32_e32 v234, v233, v231
	v_fma_f32 v235, -v230, v234, v233
	v_fmac_f32_e32 v234, v235, v231
	v_fma_f32 v230, -v230, v234, v233
	v_div_fmas_f32 v230, v230, v231, v234
	v_div_fixup_f32 v230, v230, v229, 1.0
	v_mul_f32_e32 v75, v75, v230
	v_lshlrev_b32_e32 v228, 16, v210
	v_mul_f32_e32 v228, 0xbfb8aa3b, v228
	v_exp_f32_e32 v229, v228
	s_nop 0
	v_add_f32_e32 v229, 1.0, v229
	s_nop 0
	v_div_scale_f32 v230, s[2:3], v229, v229, 1.0
	v_rcp_f32_e32 v231, v230
	s_nop 0
	v_fma_f32 v232, -v230, v231, 1.0
	v_fmac_f32_e32 v231, v232, v231
	v_div_scale_f32 v233, vcc, 1.0, v229, 1.0
	v_mul_f32_e32 v234, v233, v231
	v_fma_f32 v235, -v230, v234, v233
; __device__ __forceinline__ float b2f(u16 b) { return __uint_as_float(((uint32_t)b) << 16); }
; __device__ __forceinline__ float sigmoidf_(float x) { return 1.0f / (1.0f + __expf(-x)); }
; __device__ __forceinline__ void gemm_phase(const Ctx& cx, const GemmArgs& g_, char* shm) {
;     ...
;             } else {
;               const uint2 gv = *(const uint2*)(g.gate + (size_t)tok * NP + n0);
;               float v0 = sigmoidf_(b2f((u16)(gv.x & 0xffff))) * a[0], v1 = sigmoidf_(b2f((u16)(gv.x >> 16))) * a[1];
;               float v2 = sigmoidf_(b2f((u16)(gv.y & 0xffff))) * a[2], v3 = sigmoidf_(b2f((u16)(gv.y >> 16))) * a[3];
;               uint2* mp = (uint2*)(g.outb + (size_t)tok * DM + n0);
;               if (g.epi != EPI_BR0) {
;                 const uint2 pv = *mp;
;                 v0 += b2f((u16)(pv.x & 0xffff)); v1 += b2f((u16)(pv.x >> 16));
;                 v2 += b2f((u16)(pv.y & 0xffff)); v3 += b2f((u16)(pv.y >> 16));
;               }
;               uint2 o; o.x = pack2(v0, v1); o.y = pack2(v2, v3);
;               *mp = o;
;             }
	v_fmac_f32_e32 v234, v235, v231
	v_fma_f32 v230, -v230, v234, v233
	v_div_fmas_f32 v230, v230, v231, v234
	v_div_fixup_f32 v230, v230, v229, 1.0
	v_mul_f32_e32 v68, v68, v230
	v_and_b32_e32 v228, 0xffff0000, v210
	v_mul_f32_e32 v228, 0xbfb8aa3b, v228
	v_exp_f32_e32 v229, v228
	s_nop 0
	v_add_f32_e32 v229, 1.0, v229
	s_nop 0
	v_div_scale_f32 v230, s[2:3], v229, v229, 1.0
	v_rcp_f32_e32 v231, v230
	s_nop 0
	v_fma_f32 v232, -v230, v231, 1.0
	v_fmac_f32_e32 v231, v232, v231
	v_div_scale_f32 v233, vcc, 1.0, v229, 1.0
	v_mul_f32_e32 v234, v233, v231
	v_fma_f32 v235, -v230, v234, v233
	v_fmac_f32_e32 v234, v235, v231
	v_fma_f32 v230, -v230, v234, v233
	v_div_fmas_f32 v230, v230, v231, v234
	v_div_fixup_f32 v230, v230, v229, 1.0
	v_mul_f32_e32 v69, v69, v230
	v_lshlrev_b32_e32 v228, 16, v211
	v_mul_f32_e32 v228, 0xbfb8aa3b, v228
	v_exp_f32_e32 v229, v228
	s_nop 0
	v_add_f32_e32 v229, 1.0, v229
	s_nop 0
	v_div_scale_f32 v230, s[2:3], v229, v229, 1.0
	v_rcp_f32_e32 v231, v230
	s_nop 0
	v_fma_f32 v232, -v230, v231, 1.0
	v_fmac_f32_e32 v231, v232, v231
	v_div_scale_f32 v233, vcc, 1.0, v229, 1.0
	v_mul_f32_e32 v234, v233, v231
	v_fma_f32 v235, -v230, v234, v233
	v_fmac_f32_e32 v234, v235, v231
	v_fma_f32 v230, -v230, v234, v233
	v_div_fmas_f32 v230, v230, v231, v234
	v_div_fixup_f32 v230, v230, v229, 1.0
	v_mul_f32_e32 v70, v70, v230
	v_and_b32_e32 v228, 0xffff0000, v211
	v_mul_f32_e32 v228, 0xbfb8aa3b, v228
	v_exp_f32_e32 v229, v228
	s_nop 0
	v_add_f32_e32 v229, 1.0, v229
	s_nop 0
	v_div_scale_f32 v230, s[2:3], v229, v229, 1.0
	v_rcp_f32_e32 v231, v230
	s_nop 0
	v_fma_f32 v232, -v230, v231, 1.0
	v_fmac_f32_e32 v231, v232, v231
	v_div_scale_f32 v233, vcc, 1.0, v229, 1.0
	v_mul_f32_e32 v234, v233, v231
	v_fma_f32 v235, -v230, v234, v233
	v_fmac_f32_e32 v234, v235, v231
	v_fma_f32 v230, -v230, v234, v233
	v_div_fmas_f32 v230, v230, v231, v234
	v_div_fixup_f32 v230, v230, v229, 1.0
	v_mul_f32_e32 v71, v71, v230
	s_and_b64 vcc, exec, s[44:45]
	s_cbranch_vccz .Lmy_br_nopv_add_1_1_1
	v_lshlrev_b32_e32 v228, 16, v224
	v_add_f32_e32 v72, v72, v228
	v_and_b32_e32 v228, 0xffff0000, v224
	v_add_f32_e32 v73, v73, v228
	v_lshlrev_b32_e32 v228, 16, v225
	v_add_f32_e32 v74, v74, v228
	v_and_b32_e32 v228, 0xffff0000, v225
	v_add_f32_e32 v75, v75, v228
	v_lshlrev_b32_e32 v228, 16, v226
	v_add_f32_e32 v68, v68, v228
	v_and_b32_e32 v228, 0xffff0000, v226
	v_add_f32_e32 v69, v69, v228
	v_lshlrev_b32_e32 v228, 16, v227
	v_add_f32_e32 v70, v70, v228
	v_and_b32_e32 v228, 0xffff0000, v227
	v_add_f32_e32 v71, v71, v228
.Lmy_br_nopv_add_1_1_1:
	v_cvt_pk_bf16_f32 v240, v72, v73
	v_cvt_pk_bf16_f32 v241, v74, v75
	v_cvt_pk_bf16_f32 v242, v68, v69
	v_cvt_pk_bf16_f32 v243, v70, v71
	s_nop 1
	v_permlane16_swap_b32_e32 v240, v242
	v_permlane16_swap_b32_e32 v241, v243
	v_mov_b32_e32 v244, v240
	v_mov_b32_e32 v245, v241
	v_mov_b32_e32 v246, v242
	v_mov_b32_e32 v247, v243
	v_mov_b32_dpp v240, v236 row_ror:8 row_mask:0xf bank_mask:0x3
	v_mov_b32_dpp v241, v237 row_ror:8 row_mask:0xf bank_mask:0x3
	v_mov_b32_dpp v242, v238 row_ror:8 row_mask:0xf bank_mask:0x3
	v_mov_b32_dpp v243, v239 row_ror:8 row_mask:0xf bank_mask:0x3
	v_mov_b32_dpp v236, v244 row_ror:8 row_mask:0xf bank_mask:0xc
	v_mov_b32_dpp v237, v245 row_ror:8 row_mask:0xf bank_mask:0xc
	v_mov_b32_dpp v238, v246 row_ror:8 row_mask:0xf bank_mask:0xc
	v_mov_b32_dpp v239, v247 row_ror:8 row_mask:0xf bank_mask:0xc
	global_store_dwordx4 v[188:189], v[236:239], off offset:288
	global_store_dwordx4 v[190:191], v[240:243], off offset:288
	s_nop 1
	v_lshl_add_u64 v[188:189], v[184:185], 0, s[10:11]
	v_lshl_add_u64 v[190:191], v[188:189], 0, s[6:7]
	v_add_u32_e32 v195, 128, v194
	v_mov_b64_e32 v[244:245], s[22:23]
	v_mad_i64_i32 v[244:245], s[4:5], v195, s76, v[244:245]
	v_lshl_add_u64 v[244:245], v[186:187], 1, v[244:245]
	global_load_dwordx2 v[196:197], v[244:245], off offset:0
	global_load_dwordx2 v[198:199], v[244:245], off offset:32
	global_load_dwordx2 v[200:201], v[244:245], off offset:64
	global_load_dwordx2 v[202:203], v[244:245], off offset:96
	global_load_dwordx2 v[204:205], v[244:245], off offset:256
	global_load_dwordx2 v[206:207], v[244:245], off offset:288
	global_load_dwordx2 v[208:209], v[244:245], off offset:320
	global_load_dwordx2 v[210:211], v[244:245], off offset:352
	s_and_b64 vcc, exec, s[44:45]
	s_cbranch_vccz .Lmy_br_nopv_ld_2
	v_mov_b32_e32 v192, v195
	v_ashrrev_i32_e32 v193, 31, v195
	v_lshlrev_b64 v[192:193], 12, v[192:193]
	v_lshl_add_u64 v[192:193], s[20:21], 0, v[192:193]
	v_lshl_add_u64 v[192:193], v[186:187], 1, v[192:193]
	global_load_dwordx2 v[212:213], v[192:193], off offset:0
	global_load_dwordx2 v[214:215], v[192:193], off offset:32
	global_load_dwordx2 v[216:217], v[192:193], off offset:64
	global_load_dwordx2 v[218:219], v[192:193], off offset:96
	global_load_dwordx2 v[220:221], v[192:193], off offset:256
	global_load_dwordx2 v[222:223], v[192:193], off offset:288
	global_load_dwordx2 v[224:225], v[192:193], off offset:320
	global_load_dwordx2 v[226:227], v[192:193], off offset:352
; __device__ __forceinline__ float b2f(u16 b) { return __uint_as_float(((uint32_t)b) << 16); }
; __device__ __forceinline__ float sigmoidf_(float x) { return 1.0f / (1.0f + __expf(-x)); }
; __device__ __forceinline__ void gemm_phase(const Ctx& cx, const GemmArgs& g_, char* shm) {
;     ...
;             } else {
;               const uint2 gv = *(const uint2*)(g.gate + (size_t)tok * NP + n0);
;               float v0 = sigmoidf_(b2f((u16)(gv.x & 0xffff))) * a[0], v1 = sigmoidf_(b2f((u16)(gv.x >> 16))) * a[1];
;               float v2 = sigmoidf_(b2f((u16)(gv.y & 0xffff))) * a[2], v3 = sigmoidf_(b2f((u16)(gv.y >> 16))) * a[3];
;               uint2* mp = (uint2*)(g.outb + (size_t)tok * DM + n0);
;               if (g.epi != EPI_BR0) {
;                 const uint2 pv = *mp;
;                 v0 += b2f((u16)(pv.x & 0xffff)); v1 += b2f((u16)(pv.x >> 16));
;                 v2 += b2f((u16)(pv.y & 0xffff)); v3 += b2f((u16)(pv.y >> 16));
;               }
;               uint2 o; o.x = pack2(v0, v1); o.y = pack2(v2, v3);
;               *mp = o;
;             }
.Lmy_br_nopv_ld_2:
	s_waitcnt vmcnt(0)
	v_lshlrev_b32_e32 v228, 16, v196
	v_mul_f32_e32 v228, 0xbfb8aa3b, v228
	v_exp_f32_e32 v229, v228
	s_nop 0
	v_add_f32_e32 v229, 1.0, v229
	s_nop 0
	v_div_scale_f32 v230, s[2:3], v229, v229, 1.0
	v_rcp_f32_e32 v231, v230
	s_nop 0
	v_fma_f32 v232, -v230, v231, 1.0
	v_fmac_f32_e32 v231, v232, v231
	v_div_scale_f32 v233, vcc, 1.0, v229, 1.0
	v_mul_f32_e32 v234, v233, v231
	v_fma_f32 v235, -v230, v234, v233
	v_fmac_f32_e32 v234, v235, v231
	v_fma_f32 v230, -v230, v234, v233
	v_div_fmas_f32 v230, v230, v231, v234
	v_div_fixup_f32 v230, v230, v229, 1.0
	v_mul_f32_e32 v64, v64, v230
	v_and_b32_e32 v228, 0xffff0000, v196
	v_mul_f32_e32 v228, 0xbfb8aa3b, v228
	v_exp_f32_e32 v229, v228
	s_nop 0
	v_add_f32_e32 v229, 1.0, v229
	s_nop 0
	v_div_scale_f32 v230, s[2:3], v229, v229, 1.0
	v_rcp_f32_e32 v231, v230
	s_nop 0
	v_fma_f32 v232, -v230, v231, 1.0
	v_fmac_f32_e32 v231, v232, v231
	v_div_scale_f32 v233, vcc, 1.0, v229, 1.0
	v_mul_f32_e32 v234, v233, v231
	v_fma_f32 v235, -v230, v234, v233
	v_fmac_f32_e32 v234, v235, v231
	v_fma_f32 v230, -v230, v234, v233
	v_div_fmas_f32 v230, v230, v231, v234
	v_div_fixup_f32 v230, v230, v229, 1.0
	v_mul_f32_e32 v65, v65, v230
	v_lshlrev_b32_e32 v228, 16, v197
	v_mul_f32_e32 v228, 0xbfb8aa3b, v228
	v_exp_f32_e32 v229, v228
	s_nop 0
	v_add_f32_e32 v229, 1.0, v229
	s_nop 0
	v_div_scale_f32 v230, s[2:3], v229, v229, 1.0
	v_rcp_f32_e32 v231, v230
	s_nop 0
	v_fma_f32 v232, -v230, v231, 1.0
	v_fmac_f32_e32 v231, v232, v231
	v_div_scale_f32 v233, vcc, 1.0, v229, 1.0
	v_mul_f32_e32 v234, v233, v231
	v_fma_f32 v235, -v230, v234, v233
	v_fmac_f32_e32 v234, v235, v231
	v_fma_f32 v230, -v230, v234, v233
	v_div_fmas_f32 v230, v230, v231, v234
	v_div_fixup_f32 v230, v230, v229, 1.0
	v_mul_f32_e32 v66, v66, v230
	v_and_b32_e32 v228, 0xffff0000, v197
	v_mul_f32_e32 v228, 0xbfb8aa3b, v228
	v_exp_f32_e32 v229, v228
	s_nop 0
	v_add_f32_e32 v229, 1.0, v229
	s_nop 0
	v_div_scale_f32 v230, s[2:3], v229, v229, 1.0
	v_rcp_f32_e32 v231, v230
	s_nop 0
	v_fma_f32 v232, -v230, v231, 1.0
	v_fmac_f32_e32 v231, v232, v231
	v_div_scale_f32 v233, vcc, 1.0, v229, 1.0
	v_mul_f32_e32 v234, v233, v231
	v_fma_f32 v235, -v230, v234, v233
	v_fmac_f32_e32 v234, v235, v231
	v_fma_f32 v230, -v230, v234, v233
	v_div_fmas_f32 v230, v230, v231, v234
	v_div_fixup_f32 v230, v230, v229, 1.0
	v_mul_f32_e32 v67, v67, v230
	v_lshlrev_b32_e32 v228, 16, v198
	v_mul_f32_e32 v228, 0xbfb8aa3b, v228
	v_exp_f32_e32 v229, v228
	s_nop 0
	v_add_f32_e32 v229, 1.0, v229
	s_nop 0
	v_div_scale_f32 v230, s[2:3], v229, v229, 1.0
	v_rcp_f32_e32 v231, v230
	s_nop 0
	v_fma_f32 v232, -v230, v231, 1.0
	v_fmac_f32_e32 v231, v232, v231
	v_div_scale_f32 v233, vcc, 1.0, v229, 1.0
	v_mul_f32_e32 v234, v233, v231
	v_fma_f32 v235, -v230, v234, v233
	v_fmac_f32_e32 v234, v235, v231
	v_fma_f32 v230, -v230, v234, v233
	v_div_fmas_f32 v230, v230, v231, v234
	v_div_fixup_f32 v230, v230, v229, 1.0
	v_mul_f32_e32 v60, v60, v230
	v_and_b32_e32 v228, 0xffff0000, v198
	v_mul_f32_e32 v228, 0xbfb8aa3b, v228
	v_exp_f32_e32 v229, v228
	s_nop 0
	v_add_f32_e32 v229, 1.0, v229
	s_nop 0
	v_div_scale_f32 v230, s[2:3], v229, v229, 1.0
	v_rcp_f32_e32 v231, v230
	s_nop 0
	v_fma_f32 v232, -v230, v231, 1.0
	v_fmac_f32_e32 v231, v232, v231
	v_div_scale_f32 v233, vcc, 1.0, v229, 1.0
	v_mul_f32_e32 v234, v233, v231
	v_fma_f32 v235, -v230, v234, v233
	v_fmac_f32_e32 v234, v235, v231
	v_fma_f32 v230, -v230, v234, v233
	v_div_fmas_f32 v230, v230, v231, v234
	v_div_fixup_f32 v230, v230, v229, 1.0
	v_mul_f32_e32 v61, v61, v230
	v_lshlrev_b32_e32 v228, 16, v199
	v_mul_f32_e32 v228, 0xbfb8aa3b, v228
	v_exp_f32_e32 v229, v228
	s_nop 0
	v_add_f32_e32 v229, 1.0, v229
	s_nop 0
	v_div_scale_f32 v230, s[2:3], v229, v229, 1.0
	v_rcp_f32_e32 v231, v230
	s_nop 0
	v_fma_f32 v232, -v230, v231, 1.0
	v_fmac_f32_e32 v231, v232, v231
	v_div_scale_f32 v233, vcc, 1.0, v229, 1.0
	v_mul_f32_e32 v234, v233, v231
	v_fma_f32 v235, -v230, v234, v233
	v_fmac_f32_e32 v234, v235, v231
	v_fma_f32 v230, -v230, v234, v233
	v_div_fmas_f32 v230, v230, v231, v234
	v_div_fixup_f32 v230, v230, v229, 1.0
	v_mul_f32_e32 v62, v62, v230
	v_and_b32_e32 v228, 0xffff0000, v199
	v_mul_f32_e32 v228, 0xbfb8aa3b, v228
	v_exp_f32_e32 v229, v228
	s_nop 0
	v_add_f32_e32 v229, 1.0, v229
	s_nop 0
	v_div_scale_f32 v230, s[2:3], v229, v229, 1.0
	v_rcp_f32_e32 v231, v230
	s_nop 0
	v_fma_f32 v232, -v230, v231, 1.0
	v_fmac_f32_e32 v231, v232, v231
	v_div_scale_f32 v233, vcc, 1.0, v229, 1.0
	v_mul_f32_e32 v234, v233, v231
	v_fma_f32 v235, -v230, v234, v233
	v_fmac_f32_e32 v234, v235, v231
	v_fma_f32 v230, -v230, v234, v233
	v_div_fmas_f32 v230, v230, v231, v234
	v_div_fixup_f32 v230, v230, v229, 1.0
	v_mul_f32_e32 v63, v63, v230
	s_and_b64 vcc, exec, s[44:45]
	s_cbranch_vccz .Lmy_br_nopv_add_2_0_0
	v_lshlrev_b32_e32 v228, 16, v212
	v_add_f32_e32 v64, v64, v228
	v_and_b32_e32 v228, 0xffff0000, v212
	v_add_f32_e32 v65, v65, v228
	v_lshlrev_b32_e32 v228, 16, v213
	v_add_f32_e32 v66, v66, v228
	v_and_b32_e32 v228, 0xffff0000, v213
	v_add_f32_e32 v67, v67, v228
	v_lshlrev_b32_e32 v228, 16, v214
	v_add_f32_e32 v60, v60, v228
	v_and_b32_e32 v228, 0xffff0000, v214
	v_add_f32_e32 v61, v61, v228
	v_lshlrev_b32_e32 v228, 16, v215
	v_add_f32_e32 v62, v62, v228
	v_and_b32_e32 v228, 0xffff0000, v215
	v_add_f32_e32 v63, v63, v228
; __device__ __forceinline__ float b2f(u16 b) { return __uint_as_float(((uint32_t)b) << 16); }
; __device__ __forceinline__ float sigmoidf_(float x) { return 1.0f / (1.0f + __expf(-x)); }
; __device__ __forceinline__ void gemm_phase(const Ctx& cx, const GemmArgs& g_, char* shm) {
;     ...
;             } else {
;               const uint2 gv = *(const uint2*)(g.gate + (size_t)tok * NP + n0);
;               float v0 = sigmoidf_(b2f((u16)(gv.x & 0xffff))) * a[0], v1 = sigmoidf_(b2f((u16)(gv.x >> 16))) * a[1];
;               float v2 = sigmoidf_(b2f((u16)(gv.y & 0xffff))) * a[2], v3 = sigmoidf_(b2f((u16)(gv.y >> 16))) * a[3];
;               uint2* mp = (uint2*)(g.outb + (size_t)tok * DM + n0);
;               if (g.epi != EPI_BR0) {
;                 const uint2 pv = *mp;
;                 v0 += b2f((u16)(pv.x & 0xffff)); v1 += b2f((u16)(pv.x >> 16));
;                 v2 += b2f((u16)(pv.y & 0xffff)); v3 += b2f((u16)(pv.y >> 16));
;               }
;               uint2 o; o.x = pack2(v0, v1); o.y = pack2(v2, v3);
;               *mp = o;
;             }
.Lmy_br_nopv_add_2_0_0:
	v_cvt_pk_bf16_f32 v236, v64, v65
	v_cvt_pk_bf16_f32 v237, v66, v67
	v_cvt_pk_bf16_f32 v238, v60, v61
	v_cvt_pk_bf16_f32 v239, v62, v63
	s_nop 1
	v_permlane16_swap_b32_e32 v236, v238
	v_permlane16_swap_b32_e32 v237, v239
	v_lshlrev_b32_e32 v228, 16, v200
	v_mul_f32_e32 v228, 0xbfb8aa3b, v228
	v_exp_f32_e32 v229, v228
	s_nop 0
	v_add_f32_e32 v229, 1.0, v229
	s_nop 0
	v_div_scale_f32 v230, s[2:3], v229, v229, 1.0
	v_rcp_f32_e32 v231, v230
	s_nop 0
	v_fma_f32 v232, -v230, v231, 1.0
	v_fmac_f32_e32 v231, v232, v231
	v_div_scale_f32 v233, vcc, 1.0, v229, 1.0
	v_mul_f32_e32 v234, v233, v231
	v_fma_f32 v235, -v230, v234, v233
	v_fmac_f32_e32 v234, v235, v231
	v_fma_f32 v230, -v230, v234, v233
	v_div_fmas_f32 v230, v230, v231, v234
	v_div_fixup_f32 v230, v230, v229, 1.0
	v_mul_f32_e32 v56, v56, v230
	v_and_b32_e32 v228, 0xffff0000, v200
	v_mul_f32_e32 v228, 0xbfb8aa3b, v228
	v_exp_f32_e32 v229, v228
	s_nop 0
	v_add_f32_e32 v229, 1.0, v229
	s_nop 0
	v_div_scale_f32 v230, s[2:3], v229, v229, 1.0
	v_rcp_f32_e32 v231, v230
	s_nop 0
	v_fma_f32 v232, -v230, v231, 1.0
	v_fmac_f32_e32 v231, v232, v231
	v_div_scale_f32 v233, vcc, 1.0, v229, 1.0
	v_mul_f32_e32 v234, v233, v231
	v_fma_f32 v235, -v230, v234, v233
	v_fmac_f32_e32 v234, v235, v231
	v_fma_f32 v230, -v230, v234, v233
	v_div_fmas_f32 v230, v230, v231, v234
	v_div_fixup_f32 v230, v230, v229, 1.0
	v_mul_f32_e32 v57, v57, v230
	v_lshlrev_b32_e32 v228, 16, v201
	v_mul_f32_e32 v228, 0xbfb8aa3b, v228
	v_exp_f32_e32 v229, v228
	s_nop 0
	v_add_f32_e32 v229, 1.0, v229
	s_nop 0
	v_div_scale_f32 v230, s[2:3], v229, v229, 1.0
	v_rcp_f32_e32 v231, v230
	s_nop 0
	v_fma_f32 v232, -v230, v231, 1.0
	v_fmac_f32_e32 v231, v232, v231
	v_div_scale_f32 v233, vcc, 1.0, v229, 1.0
	v_mul_f32_e32 v234, v233, v231
	v_fma_f32 v235, -v230, v234, v233
	v_fmac_f32_e32 v234, v235, v231
	v_fma_f32 v230, -v230, v234, v233
	v_div_fmas_f32 v230, v230, v231, v234
	v_div_fixup_f32 v230, v230, v229, 1.0
	v_mul_f32_e32 v58, v58, v230
	v_and_b32_e32 v228, 0xffff0000, v201
	v_mul_f32_e32 v228, 0xbfb8aa3b, v228
	v_exp_f32_e32 v229, v228
	s_nop 0
	v_add_f32_e32 v229, 1.0, v229
	s_nop 0
	v_div_scale_f32 v230, s[2:3], v229, v229, 1.0
	v_rcp_f32_e32 v231, v230
	s_nop 0
	v_fma_f32 v232, -v230, v231, 1.0
	v_fmac_f32_e32 v231, v232, v231
	v_div_scale_f32 v233, vcc, 1.0, v229, 1.0
	v_mul_f32_e32 v234, v233, v231
	v_fma_f32 v235, -v230, v234, v233
	v_fmac_f32_e32 v234, v235, v231
	v_fma_f32 v230, -v230, v234, v233
	v_div_fmas_f32 v230, v230, v231, v234
	v_div_fixup_f32 v230, v230, v229, 1.0
	v_mul_f32_e32 v59, v59, v230
	v_lshlrev_b32_e32 v228, 16, v202
	v_mul_f32_e32 v228, 0xbfb8aa3b, v228
	v_exp_f32_e32 v229, v228
	s_nop 0
	v_add_f32_e32 v229, 1.0, v229
	s_nop 0
	v_div_scale_f32 v230, s[2:3], v229, v229, 1.0
	v_rcp_f32_e32 v231, v230
	s_nop 0
	v_fma_f32 v232, -v230, v231, 1.0
	v_fmac_f32_e32 v231, v232, v231
	v_div_scale_f32 v233, vcc, 1.0, v229, 1.0
	v_mul_f32_e32 v234, v233, v231
	v_fma_f32 v235, -v230, v234, v233
	v_fmac_f32_e32 v234, v235, v231
	v_fma_f32 v230, -v230, v234, v233
	v_div_fmas_f32 v230, v230, v231, v234
	v_div_fixup_f32 v230, v230, v229, 1.0
	v_mul_f32_e32 v52, v52, v230
	v_and_b32_e32 v228, 0xffff0000, v202
	v_mul_f32_e32 v228, 0xbfb8aa3b, v228
	v_exp_f32_e32 v229, v228
	s_nop 0
	v_add_f32_e32 v229, 1.0, v229
	s_nop 0
	v_div_scale_f32 v230, s[2:3], v229, v229, 1.0
	v_rcp_f32_e32 v231, v230
	s_nop 0
	v_fma_f32 v232, -v230, v231, 1.0
	v_fmac_f32_e32 v231, v232, v231
	v_div_scale_f32 v233, vcc, 1.0, v229, 1.0
	v_mul_f32_e32 v234, v233, v231
	v_fma_f32 v235, -v230, v234, v233
	v_fmac_f32_e32 v234, v235, v231
	v_fma_f32 v230, -v230, v234, v233
	v_div_fmas_f32 v230, v230, v231, v234
	v_div_fixup_f32 v230, v230, v229, 1.0
	v_mul_f32_e32 v53, v53, v230
	v_lshlrev_b32_e32 v228, 16, v203
	v_mul_f32_e32 v228, 0xbfb8aa3b, v228
	v_exp_f32_e32 v229, v228
	s_nop 0
	v_add_f32_e32 v229, 1.0, v229
	s_nop 0
	v_div_scale_f32 v230, s[2:3], v229, v229, 1.0
	v_rcp_f32_e32 v231, v230
	s_nop 0
	v_fma_f32 v232, -v230, v231, 1.0
	v_fmac_f32_e32 v231, v232, v231
	v_div_scale_f32 v233, vcc, 1.0, v229, 1.0
	v_mul_f32_e32 v234, v233, v231
	v_fma_f32 v235, -v230, v234, v233
	v_fmac_f32_e32 v234, v235, v231
	v_fma_f32 v230, -v230, v234, v233
	v_div_fmas_f32 v230, v230, v231, v234
	v_div_fixup_f32 v230, v230, v229, 1.0
	v_mul_f32_e32 v54, v54, v230
	v_and_b32_e32 v228, 0xffff0000, v203
	v_mul_f32_e32 v228, 0xbfb8aa3b, v228
	v_exp_f32_e32 v229, v228
	s_nop 0
	v_add_f32_e32 v229, 1.0, v229
	s_nop 0
	v_div_scale_f32 v230, s[2:3], v229, v229, 1.0
	v_rcp_f32_e32 v231, v230
	s_nop 0
	v_fma_f32 v232, -v230, v231, 1.0
	v_fmac_f32_e32 v231, v232, v231
	v_div_scale_f32 v233, vcc, 1.0, v229, 1.0
	v_mul_f32_e32 v234, v233, v231
	v_fma_f32 v235, -v230, v234, v233
	v_fmac_f32_e32 v234, v235, v231
	v_fma_f32 v230, -v230, v234, v233
	v_div_fmas_f32 v230, v230, v231, v234
	v_div_fixup_f32 v230, v230, v229, 1.0
	v_mul_f32_e32 v55, v55, v230
	s_and_b64 vcc, exec, s[44:45]
	s_cbranch_vccz .Lmy_br_nopv_add_2_0_1
	v_lshlrev_b32_e32 v228, 16, v216
	v_add_f32_e32 v56, v56, v228
	v_and_b32_e32 v228, 0xffff0000, v216
	v_add_f32_e32 v57, v57, v228
	v_lshlrev_b32_e32 v228, 16, v217
	v_add_f32_e32 v58, v58, v228
	v_and_b32_e32 v228, 0xffff0000, v217
	v_add_f32_e32 v59, v59, v228
	v_lshlrev_b32_e32 v228, 16, v218
	v_add_f32_e32 v52, v52, v228
	v_and_b32_e32 v228, 0xffff0000, v218
	v_add_f32_e32 v53, v53, v228
	v_lshlrev_b32_e32 v228, 16, v219
	v_add_f32_e32 v54, v54, v228
	v_and_b32_e32 v228, 0xffff0000, v219
	v_add_f32_e32 v55, v55, v228
; __device__ __forceinline__ float b2f(u16 b) { return __uint_as_float(((uint32_t)b) << 16); }
; __device__ __forceinline__ float sigmoidf_(float x) { return 1.0f / (1.0f + __expf(-x)); }
; __device__ __forceinline__ void gemm_phase(const Ctx& cx, const GemmArgs& g_, char* shm) {
;     ...
;             } else {
;               const uint2 gv = *(const uint2*)(g.gate + (size_t)tok * NP + n0);
;               float v0 = sigmoidf_(b2f((u16)(gv.x & 0xffff))) * a[0], v1 = sigmoidf_(b2f((u16)(gv.x >> 16))) * a[1];
;               float v2 = sigmoidf_(b2f((u16)(gv.y & 0xffff))) * a[2], v3 = sigmoidf_(b2f((u16)(gv.y >> 16))) * a[3];
;               uint2* mp = (uint2*)(g.outb + (size_t)tok * DM + n0);
;               if (g.epi != EPI_BR0) {
;                 const uint2 pv = *mp;
;                 v0 += b2f((u16)(pv.x & 0xffff)); v1 += b2f((u16)(pv.x >> 16));
;                 v2 += b2f((u16)(pv.y & 0xffff)); v3 += b2f((u16)(pv.y >> 16));
;               }
;               uint2 o; o.x = pack2(v0, v1); o.y = pack2(v2, v3);
;               *mp = o;
;             }
.Lmy_br_nopv_add_2_0_1:
	v_cvt_pk_bf16_f32 v240, v56, v57
	v_cvt_pk_bf16_f32 v241, v58, v59
	v_cvt_pk_bf16_f32 v242, v52, v53
	v_cvt_pk_bf16_f32 v243, v54, v55
	s_nop 1
	v_permlane16_swap_b32_e32 v240, v242
	v_permlane16_swap_b32_e32 v241, v243
	v_mov_b32_e32 v244, v240
	v_mov_b32_e32 v245, v241
	v_mov_b32_e32 v246, v242
	v_mov_b32_e32 v247, v243
	v_mov_b32_dpp v240, v236 row_ror:8 row_mask:0xf bank_mask:0x3
	v_mov_b32_dpp v241, v237 row_ror:8 row_mask:0xf bank_mask:0x3
	v_mov_b32_dpp v242, v238 row_ror:8 row_mask:0xf bank_mask:0x3
	v_mov_b32_dpp v243, v239 row_ror:8 row_mask:0xf bank_mask:0x3
	v_mov_b32_dpp v236, v244 row_ror:8 row_mask:0xf bank_mask:0xc
	v_mov_b32_dpp v237, v245 row_ror:8 row_mask:0xf bank_mask:0xc
	v_mov_b32_dpp v238, v246 row_ror:8 row_mask:0xf bank_mask:0xc
	v_mov_b32_dpp v239, v247 row_ror:8 row_mask:0xf bank_mask:0xc
	global_store_dwordx4 v[188:189], v[236:239], off offset:32
	global_store_dwordx4 v[190:191], v[240:243], off offset:32
	s_nop 1
	v_lshlrev_b32_e32 v228, 16, v204
	v_mul_f32_e32 v228, 0xbfb8aa3b, v228
	v_exp_f32_e32 v229, v228
	s_nop 0
	v_add_f32_e32 v229, 1.0, v229
	s_nop 0
	v_div_scale_f32 v230, s[2:3], v229, v229, 1.0
	v_rcp_f32_e32 v231, v230
	s_nop 0
	v_fma_f32 v232, -v230, v231, 1.0
	v_fmac_f32_e32 v231, v232, v231
	v_div_scale_f32 v233, vcc, 1.0, v229, 1.0
	v_mul_f32_e32 v234, v233, v231
	v_fma_f32 v235, -v230, v234, v233
	v_fmac_f32_e32 v234, v235, v231
	v_fma_f32 v230, -v230, v234, v233
	v_div_fmas_f32 v230, v230, v231, v234
	v_div_fixup_f32 v230, v230, v229, 1.0
	v_mul_f32_e32 v48, v48, v230
	v_and_b32_e32 v228, 0xffff0000, v204
	v_mul_f32_e32 v228, 0xbfb8aa3b, v228
	v_exp_f32_e32 v229, v228
	s_nop 0
	v_add_f32_e32 v229, 1.0, v229
	s_nop 0
	v_div_scale_f32 v230, s[2:3], v229, v229, 1.0
	v_rcp_f32_e32 v231, v230
	s_nop 0
	v_fma_f32 v232, -v230, v231, 1.0
	v_fmac_f32_e32 v231, v232, v231
	v_div_scale_f32 v233, vcc, 1.0, v229, 1.0
	v_mul_f32_e32 v234, v233, v231
	v_fma_f32 v235, -v230, v234, v233
	v_fmac_f32_e32 v234, v235, v231
	v_fma_f32 v230, -v230, v234, v233
	v_div_fmas_f32 v230, v230, v231, v234
	v_div_fixup_f32 v230, v230, v229, 1.0
	v_mul_f32_e32 v49, v49, v230
	v_lshlrev_b32_e32 v228, 16, v205
	v_mul_f32_e32 v228, 0xbfb8aa3b, v228
	v_exp_f32_e32 v229, v228
	s_nop 0
	v_add_f32_e32 v229, 1.0, v229
	s_nop 0
	v_div_scale_f32 v230, s[2:3], v229, v229, 1.0
	v_rcp_f32_e32 v231, v230
	s_nop 0
	v_fma_f32 v232, -v230, v231, 1.0
	v_fmac_f32_e32 v231, v232, v231
	v_div_scale_f32 v233, vcc, 1.0, v229, 1.0
	v_mul_f32_e32 v234, v233, v231
	v_fma_f32 v235, -v230, v234, v233
	v_fmac_f32_e32 v234, v235, v231
	v_fma_f32 v230, -v230, v234, v233
	v_div_fmas_f32 v230, v230, v231, v234
	v_div_fixup_f32 v230, v230, v229, 1.0
	v_mul_f32_e32 v50, v50, v230
	v_and_b32_e32 v228, 0xffff0000, v205
	v_mul_f32_e32 v228, 0xbfb8aa3b, v228
	v_exp_f32_e32 v229, v228
	s_nop 0
	v_add_f32_e32 v229, 1.0, v229
	s_nop 0
	v_div_scale_f32 v230, s[2:3], v229, v229, 1.0
	v_rcp_f32_e32 v231, v230
	s_nop 0
	v_fma_f32 v232, -v230, v231, 1.0
	v_fmac_f32_e32 v231, v232, v231
	v_div_scale_f32 v233, vcc, 1.0, v229, 1.0
	v_mul_f32_e32 v234, v233, v231
	v_fma_f32 v235, -v230, v234, v233
	v_fmac_f32_e32 v234, v235, v231
	v_fma_f32 v230, -v230, v234, v233
	v_div_fmas_f32 v230, v230, v231, v234
	v_div_fixup_f32 v230, v230, v229, 1.0
	v_mul_f32_e32 v51, v51, v230
	v_lshlrev_b32_e32 v228, 16, v206
	v_mul_f32_e32 v228, 0xbfb8aa3b, v228
	v_exp_f32_e32 v229, v228
	s_nop 0
	v_add_f32_e32 v229, 1.0, v229
	s_nop 0
	v_div_scale_f32 v230, s[2:3], v229, v229, 1.0
	v_rcp_f32_e32 v231, v230
	s_nop 0
	v_fma_f32 v232, -v230, v231, 1.0
	v_fmac_f32_e32 v231, v232, v231
	v_div_scale_f32 v233, vcc, 1.0, v229, 1.0
	v_mul_f32_e32 v234, v233, v231
	v_fma_f32 v235, -v230, v234, v233
	v_fmac_f32_e32 v234, v235, v231
	v_fma_f32 v230, -v230, v234, v233
	v_div_fmas_f32 v230, v230, v231, v234
	v_div_fixup_f32 v230, v230, v229, 1.0
	v_mul_f32_e32 v44, v44, v230
	v_and_b32_e32 v228, 0xffff0000, v206
	v_mul_f32_e32 v228, 0xbfb8aa3b, v228
	v_exp_f32_e32 v229, v228
	s_nop 0
	v_add_f32_e32 v229, 1.0, v229
	s_nop 0
	v_div_scale_f32 v230, s[2:3], v229, v229, 1.0
	v_rcp_f32_e32 v231, v230
	s_nop 0
	v_fma_f32 v232, -v230, v231, 1.0
	v_fmac_f32_e32 v231, v232, v231
	v_div_scale_f32 v233, vcc, 1.0, v229, 1.0
	v_mul_f32_e32 v234, v233, v231
	v_fma_f32 v235, -v230, v234, v233
	v_fmac_f32_e32 v234, v235, v231
	v_fma_f32 v230, -v230, v234, v233
	v_div_fmas_f32 v230, v230, v231, v234
	v_div_fixup_f32 v230, v230, v229, 1.0
	v_mul_f32_e32 v45, v45, v230
	v_lshlrev_b32_e32 v228, 16, v207
	v_mul_f32_e32 v228, 0xbfb8aa3b, v228
	v_exp_f32_e32 v229, v228
	s_nop 0
	v_add_f32_e32 v229, 1.0, v229
	s_nop 0
	v_div_scale_f32 v230, s[2:3], v229, v229, 1.0
	v_rcp_f32_e32 v231, v230
	s_nop 0
	v_fma_f32 v232, -v230, v231, 1.0
	v_fmac_f32_e32 v231, v232, v231
	v_div_scale_f32 v233, vcc, 1.0, v229, 1.0
	v_mul_f32_e32 v234, v233, v231
	v_fma_f32 v235, -v230, v234, v233
	v_fmac_f32_e32 v234, v235, v231
	v_fma_f32 v230, -v230, v234, v233
	v_div_fmas_f32 v230, v230, v231, v234
	v_div_fixup_f32 v230, v230, v229, 1.0
	v_mul_f32_e32 v46, v46, v230
	v_and_b32_e32 v228, 0xffff0000, v207
	v_mul_f32_e32 v228, 0xbfb8aa3b, v228
	v_exp_f32_e32 v229, v228
	s_nop 0
	v_add_f32_e32 v229, 1.0, v229
	s_nop 0
	v_div_scale_f32 v230, s[2:3], v229, v229, 1.0
	v_rcp_f32_e32 v231, v230
	s_nop 0
	v_fma_f32 v232, -v230, v231, 1.0
	v_fmac_f32_e32 v231, v232, v231
	v_div_scale_f32 v233, vcc, 1.0, v229, 1.0
	v_mul_f32_e32 v234, v233, v231
	v_fma_f32 v235, -v230, v234, v233
	v_fmac_f32_e32 v234, v235, v231
	v_fma_f32 v230, -v230, v234, v233
	v_div_fmas_f32 v230, v230, v231, v234
	v_div_fixup_f32 v230, v230, v229, 1.0
	v_mul_f32_e32 v47, v47, v230
	s_and_b64 vcc, exec, s[44:45]
	s_cbranch_vccz .Lmy_br_nopv_add_2_1_0
	v_lshlrev_b32_e32 v228, 16, v220
	v_add_f32_e32 v48, v48, v228
	v_and_b32_e32 v228, 0xffff0000, v220
	v_add_f32_e32 v49, v49, v228
	v_lshlrev_b32_e32 v228, 16, v221
	v_add_f32_e32 v50, v50, v228
	v_and_b32_e32 v228, 0xffff0000, v221
	v_add_f32_e32 v51, v51, v228
	v_lshlrev_b32_e32 v228, 16, v222
	v_add_f32_e32 v44, v44, v228
	v_and_b32_e32 v228, 0xffff0000, v222
	v_add_f32_e32 v45, v45, v228
	v_lshlrev_b32_e32 v228, 16, v223
	v_add_f32_e32 v46, v46, v228
	v_and_b32_e32 v228, 0xffff0000, v223
	v_add_f32_e32 v47, v47, v228
; __device__ __forceinline__ float b2f(u16 b) { return __uint_as_float(((uint32_t)b) << 16); }
; __device__ __forceinline__ float sigmoidf_(float x) { return 1.0f / (1.0f + __expf(-x)); }
; __device__ __forceinline__ void gemm_phase(const Ctx& cx, const GemmArgs& g_, char* shm) {
;     ...
;             } else {
;               const uint2 gv = *(const uint2*)(g.gate + (size_t)tok * NP + n0);
;               float v0 = sigmoidf_(b2f((u16)(gv.x & 0xffff))) * a[0], v1 = sigmoidf_(b2f((u16)(gv.x >> 16))) * a[1];
;               float v2 = sigmoidf_(b2f((u16)(gv.y & 0xffff))) * a[2], v3 = sigmoidf_(b2f((u16)(gv.y >> 16))) * a[3];
;               uint2* mp = (uint2*)(g.outb + (size_t)tok * DM + n0);
;               if (g.epi != EPI_BR0) {
;                 const uint2 pv = *mp;
;                 v0 += b2f((u16)(pv.x & 0xffff)); v1 += b2f((u16)(pv.x >> 16));
;                 v2 += b2f((u16)(pv.y & 0xffff)); v3 += b2f((u16)(pv.y >> 16));
;               }
;               uint2 o; o.x = pack2(v0, v1); o.y = pack2(v2, v3);
;               *mp = o;
;             }
.Lmy_br_nopv_add_2_1_0:
	v_cvt_pk_bf16_f32 v236, v48, v49
	v_cvt_pk_bf16_f32 v237, v50, v51
	v_cvt_pk_bf16_f32 v238, v44, v45
	v_cvt_pk_bf16_f32 v239, v46, v47
	s_nop 1
	v_permlane16_swap_b32_e32 v236, v238
	v_permlane16_swap_b32_e32 v237, v239
	v_lshlrev_b32_e32 v228, 16, v208
	v_mul_f32_e32 v228, 0xbfb8aa3b, v228
	v_exp_f32_e32 v229, v228
	s_nop 0
	v_add_f32_e32 v229, 1.0, v229
	s_nop 0
	v_div_scale_f32 v230, s[2:3], v229, v229, 1.0
	v_rcp_f32_e32 v231, v230
	s_nop 0
	v_fma_f32 v232, -v230, v231, 1.0
	v_fmac_f32_e32 v231, v232, v231
	v_div_scale_f32 v233, vcc, 1.0, v229, 1.0
	v_mul_f32_e32 v234, v233, v231
	v_fma_f32 v235, -v230, v234, v233
	v_fmac_f32_e32 v234, v235, v231
	v_fma_f32 v230, -v230, v234, v233
	v_div_fmas_f32 v230, v230, v231, v234
	v_div_fixup_f32 v230, v230, v229, 1.0
	v_mul_f32_e32 v40, v40, v230
	v_and_b32_e32 v228, 0xffff0000, v208
	v_mul_f32_e32 v228, 0xbfb8aa3b, v228
	v_exp_f32_e32 v229, v228
	s_nop 0
	v_add_f32_e32 v229, 1.0, v229
	s_nop 0
	v_div_scale_f32 v230, s[2:3], v229, v229, 1.0
	v_rcp_f32_e32 v231, v230
	s_nop 0
	v_fma_f32 v232, -v230, v231, 1.0
	v_fmac_f32_e32 v231, v232, v231
	v_div_scale_f32 v233, vcc, 1.0, v229, 1.0
	v_mul_f32_e32 v234, v233, v231
	v_fma_f32 v235, -v230, v234, v233
	v_fmac_f32_e32 v234, v235, v231
	v_fma_f32 v230, -v230, v234, v233
	v_div_fmas_f32 v230, v230, v231, v234
	v_div_fixup_f32 v230, v230, v229, 1.0
	v_mul_f32_e32 v41, v41, v230
	v_lshlrev_b32_e32 v228, 16, v209
	v_mul_f32_e32 v228, 0xbfb8aa3b, v228
	v_exp_f32_e32 v229, v228
	s_nop 0
	v_add_f32_e32 v229, 1.0, v229
	s_nop 0
	v_div_scale_f32 v230, s[2:3], v229, v229, 1.0
	v_rcp_f32_e32 v231, v230
	s_nop 0
	v_fma_f32 v232, -v230, v231, 1.0
	v_fmac_f32_e32 v231, v232, v231
	v_div_scale_f32 v233, vcc, 1.0, v229, 1.0
	v_mul_f32_e32 v234, v233, v231
	v_fma_f32 v235, -v230, v234, v233
	v_fmac_f32_e32 v234, v235, v231
	v_fma_f32 v230, -v230, v234, v233
	v_div_fmas_f32 v230, v230, v231, v234
	v_div_fixup_f32 v230, v230, v229, 1.0
	v_mul_f32_e32 v42, v42, v230
	v_and_b32_e32 v228, 0xffff0000, v209
	v_mul_f32_e32 v228, 0xbfb8aa3b, v228
	v_exp_f32_e32 v229, v228
	s_nop 0
	v_add_f32_e32 v229, 1.0, v229
	s_nop 0
	v_div_scale_f32 v230, s[2:3], v229, v229, 1.0
	v_rcp_f32_e32 v231, v230
	s_nop 0
	v_fma_f32 v232, -v230, v231, 1.0
	v_fmac_f32_e32 v231, v232, v231
	v_div_scale_f32 v233, vcc, 1.0, v229, 1.0
	v_mul_f32_e32 v234, v233, v231
	v_fma_f32 v235, -v230, v234, v233
	v_fmac_f32_e32 v234, v235, v231
	v_fma_f32 v230, -v230, v234, v233
	v_div_fmas_f32 v230, v230, v231, v234
	v_div_fixup_f32 v230, v230, v229, 1.0
	v_mul_f32_e32 v43, v43, v230
	v_lshlrev_b32_e32 v228, 16, v210
	v_mul_f32_e32 v228, 0xbfb8aa3b, v228
	v_exp_f32_e32 v229, v228
	s_nop 0
	v_add_f32_e32 v229, 1.0, v229
	s_nop 0
	v_div_scale_f32 v230, s[2:3], v229, v229, 1.0
	v_rcp_f32_e32 v231, v230
	s_nop 0
	v_fma_f32 v232, -v230, v231, 1.0
	v_fmac_f32_e32 v231, v232, v231
	v_div_scale_f32 v233, vcc, 1.0, v229, 1.0
	v_mul_f32_e32 v234, v233, v231
	v_fma_f32 v235, -v230, v234, v233
	v_fmac_f32_e32 v234, v235, v231
	v_fma_f32 v230, -v230, v234, v233
	v_div_fmas_f32 v230, v230, v231, v234
	v_div_fixup_f32 v230, v230, v229, 1.0
	v_mul_f32_e32 v36, v36, v230
	v_and_b32_e32 v228, 0xffff0000, v210
	v_mul_f32_e32 v228, 0xbfb8aa3b, v228
	v_exp_f32_e32 v229, v228
	s_nop 0
	v_add_f32_e32 v229, 1.0, v229
	s_nop 0
	v_div_scale_f32 v230, s[2:3], v229, v229, 1.0
	v_rcp_f32_e32 v231, v230
	s_nop 0
	v_fma_f32 v232, -v230, v231, 1.0
	v_fmac_f32_e32 v231, v232, v231
	v_div_scale_f32 v233, vcc, 1.0, v229, 1.0
	v_mul_f32_e32 v234, v233, v231
	v_fma_f32 v235, -v230, v234, v233
	v_fmac_f32_e32 v234, v235, v231
	v_fma_f32 v230, -v230, v234, v233
	v_div_fmas_f32 v230, v230, v231, v234
	v_div_fixup_f32 v230, v230, v229, 1.0
	v_mul_f32_e32 v37, v37, v230
	v_lshlrev_b32_e32 v228, 16, v211
	v_mul_f32_e32 v228, 0xbfb8aa3b, v228
	v_exp_f32_e32 v229, v228
	s_nop 0
	v_add_f32_e32 v229, 1.0, v229
	s_nop 0
	v_div_scale_f32 v230, s[2:3], v229, v229, 1.0
	v_rcp_f32_e32 v231, v230
	s_nop 0
	v_fma_f32 v232, -v230, v231, 1.0
	v_fmac_f32_e32 v231, v232, v231
	v_div_scale_f32 v233, vcc, 1.0, v229, 1.0
	v_mul_f32_e32 v234, v233, v231
	v_fma_f32 v235, -v230, v234, v233
	v_fmac_f32_e32 v234, v235, v231
	v_fma_f32 v230, -v230, v234, v233
	v_div_fmas_f32 v230, v230, v231, v234
	v_div_fixup_f32 v230, v230, v229, 1.0
	v_mul_f32_e32 v38, v38, v230
	v_and_b32_e32 v228, 0xffff0000, v211
	v_mul_f32_e32 v228, 0xbfb8aa3b, v228
	v_exp_f32_e32 v229, v228
	s_nop 0
	v_add_f32_e32 v229, 1.0, v229
	s_nop 0
	v_div_scale_f32 v230, s[2:3], v229, v229, 1.0
	v_rcp_f32_e32 v231, v230
	s_nop 0
	v_fma_f32 v232, -v230, v231, 1.0
	v_fmac_f32_e32 v231, v232, v231
	v_div_scale_f32 v233, vcc, 1.0, v229, 1.0
	v_mul_f32_e32 v234, v233, v231
	v_fma_f32 v235, -v230, v234, v233
	v_fmac_f32_e32 v234, v235, v231
	v_fma_f32 v230, -v230, v234, v233
	v_div_fmas_f32 v230, v230, v231, v234
	v_div_fixup_f32 v230, v230, v229, 1.0
	v_mul_f32_e32 v39, v39, v230
	s_and_b64 vcc, exec, s[44:45]
	s_cbranch_vccz .Lmy_br_nopv_add_2_1_1
	v_lshlrev_b32_e32 v228, 16, v224
	v_add_f32_e32 v40, v40, v228
	v_and_b32_e32 v228, 0xffff0000, v224
	v_add_f32_e32 v41, v41, v228
	v_lshlrev_b32_e32 v228, 16, v225
	v_add_f32_e32 v42, v42, v228
	v_and_b32_e32 v228, 0xffff0000, v225
	v_add_f32_e32 v43, v43, v228
	v_lshlrev_b32_e32 v228, 16, v226
	v_add_f32_e32 v36, v36, v228
	v_and_b32_e32 v228, 0xffff0000, v226
	v_add_f32_e32 v37, v37, v228
	v_lshlrev_b32_e32 v228, 16, v227
	v_add_f32_e32 v38, v38, v228
	v_and_b32_e32 v228, 0xffff0000, v227
	v_add_f32_e32 v39, v39, v228
; __device__ __forceinline__ float b2f(u16 b) { return __uint_as_float(((uint32_t)b) << 16); }
; __device__ __forceinline__ float sigmoidf_(float x) { return 1.0f / (1.0f + __expf(-x)); }
; __device__ __forceinline__ void gemm_phase(const Ctx& cx, const GemmArgs& g_, char* shm) {
;     ...
;             } else {
;               const uint2 gv = *(const uint2*)(g.gate + (size_t)tok * NP + n0);
;               float v0 = sigmoidf_(b2f((u16)(gv.x & 0xffff))) * a[0], v1 = sigmoidf_(b2f((u16)(gv.x >> 16))) * a[1];
;               float v2 = sigmoidf_(b2f((u16)(gv.y & 0xffff))) * a[2], v3 = sigmoidf_(b2f((u16)(gv.y >> 16))) * a[3];
;               uint2* mp = (uint2*)(g.outb + (size_t)tok * DM + n0);
;               if (g.epi != EPI_BR0) {
;                 const uint2 pv = *mp;
;                 v0 += b2f((u16)(pv.x & 0xffff)); v1 += b2f((u16)(pv.x >> 16));
;                 v2 += b2f((u16)(pv.y & 0xffff)); v3 += b2f((u16)(pv.y >> 16));
;               }
;               uint2 o; o.x = pack2(v0, v1); o.y = pack2(v2, v3);
;               *mp = o;
;             }
.Lmy_br_nopv_add_2_1_1:
	v_cvt_pk_bf16_f32 v240, v40, v41
	v_cvt_pk_bf16_f32 v241, v42, v43
	v_cvt_pk_bf16_f32 v242, v36, v37
	v_cvt_pk_bf16_f32 v243, v38, v39
	s_nop 1
	v_permlane16_swap_b32_e32 v240, v242
	v_permlane16_swap_b32_e32 v241, v243
	v_mov_b32_e32 v244, v240
	v_mov_b32_e32 v245, v241
	v_mov_b32_e32 v246, v242
	v_mov_b32_e32 v247, v243
	v_mov_b32_dpp v240, v236 row_ror:8 row_mask:0xf bank_mask:0x3
	v_mov_b32_dpp v241, v237 row_ror:8 row_mask:0xf bank_mask:0x3
	v_mov_b32_dpp v242, v238 row_ror:8 row_mask:0xf bank_mask:0x3
	v_mov_b32_dpp v243, v239 row_ror:8 row_mask:0xf bank_mask:0x3
	v_mov_b32_dpp v236, v244 row_ror:8 row_mask:0xf bank_mask:0xc
	v_mov_b32_dpp v237, v245 row_ror:8 row_mask:0xf bank_mask:0xc
	v_mov_b32_dpp v238, v246 row_ror:8 row_mask:0xf bank_mask:0xc
	v_mov_b32_dpp v239, v247 row_ror:8 row_mask:0xf bank_mask:0xc
	global_store_dwordx4 v[188:189], v[236:239], off offset:288
	global_store_dwordx4 v[190:191], v[240:243], off offset:288
	s_nop 1
	v_lshl_add_u64 v[188:189], v[184:185], 0, s[10:11]
	v_lshl_add_u64 v[188:189], v[188:189], 0, s[8:9]
	v_lshl_add_u64 v[190:191], v[188:189], 0, s[6:7]
	v_add_u32_e32 v195, 144, v194
	v_mov_b64_e32 v[244:245], s[22:23]
	v_mad_i64_i32 v[244:245], s[4:5], v195, s76, v[244:245]
	v_lshl_add_u64 v[244:245], v[186:187], 1, v[244:245]
	global_load_dwordx2 v[196:197], v[244:245], off offset:0
	global_load_dwordx2 v[198:199], v[244:245], off offset:32
	global_load_dwordx2 v[200:201], v[244:245], off offset:64
	global_load_dwordx2 v[202:203], v[244:245], off offset:96
	global_load_dwordx2 v[204:205], v[244:245], off offset:256
	global_load_dwordx2 v[206:207], v[244:245], off offset:288
	global_load_dwordx2 v[208:209], v[244:245], off offset:320
	global_load_dwordx2 v[210:211], v[244:245], off offset:352
	s_and_b64 vcc, exec, s[44:45]
	s_cbranch_vccz .Lmy_br_nopv_ld_3
	v_mov_b32_e32 v192, v195
	v_ashrrev_i32_e32 v193, 31, v195
	v_lshlrev_b64 v[192:193], 12, v[192:193]
	v_lshl_add_u64 v[192:193], s[20:21], 0, v[192:193]
	v_lshl_add_u64 v[192:193], v[186:187], 1, v[192:193]
	global_load_dwordx2 v[212:213], v[192:193], off offset:0
	global_load_dwordx2 v[214:215], v[192:193], off offset:32
	global_load_dwordx2 v[216:217], v[192:193], off offset:64
	global_load_dwordx2 v[218:219], v[192:193], off offset:96
	global_load_dwordx2 v[220:221], v[192:193], off offset:256
	global_load_dwordx2 v[222:223], v[192:193], off offset:288
	global_load_dwordx2 v[224:225], v[192:193], off offset:320
	global_load_dwordx2 v[226:227], v[192:193], off offset:352
.Lmy_br_nopv_ld_3:
	s_waitcnt vmcnt(0)
	v_lshlrev_b32_e32 v228, 16, v196
	v_mul_f32_e32 v228, 0xbfb8aa3b, v228
	v_exp_f32_e32 v229, v228
	s_nop 0
	v_add_f32_e32 v229, 1.0, v229
	s_nop 0
	v_div_scale_f32 v230, s[2:3], v229, v229, 1.0
	v_rcp_f32_e32 v231, v230
	s_nop 0
	v_fma_f32 v232, -v230, v231, 1.0
	v_fmac_f32_e32 v231, v232, v231
	v_div_scale_f32 v233, vcc, 1.0, v229, 1.0
	v_mul_f32_e32 v234, v233, v231
	v_fma_f32 v235, -v230, v234, v233
	v_fmac_f32_e32 v234, v235, v231
	v_fma_f32 v230, -v230, v234, v233
	v_div_fmas_f32 v230, v230, v231, v234
	v_div_fixup_f32 v230, v230, v229, 1.0
	v_mul_f32_e32 v32, v32, v230
	v_and_b32_e32 v228, 0xffff0000, v196
	v_mul_f32_e32 v228, 0xbfb8aa3b, v228
	v_exp_f32_e32 v229, v228
	s_nop 0
	v_add_f32_e32 v229, 1.0, v229
	s_nop 0
	v_div_scale_f32 v230, s[2:3], v229, v229, 1.0
	v_rcp_f32_e32 v231, v230
	s_nop 0
	v_fma_f32 v232, -v230, v231, 1.0
	v_fmac_f32_e32 v231, v232, v231
	v_div_scale_f32 v233, vcc, 1.0, v229, 1.0
	v_mul_f32_e32 v234, v233, v231
	v_fma_f32 v235, -v230, v234, v233
	v_fmac_f32_e32 v234, v235, v231
	v_fma_f32 v230, -v230, v234, v233
	v_div_fmas_f32 v230, v230, v231, v234
	v_div_fixup_f32 v230, v230, v229, 1.0
	v_mul_f32_e32 v33, v33, v230
	v_lshlrev_b32_e32 v228, 16, v197
	v_mul_f32_e32 v228, 0xbfb8aa3b, v228
	v_exp_f32_e32 v229, v228
	s_nop 0
	v_add_f32_e32 v229, 1.0, v229
	s_nop 0
	v_div_scale_f32 v230, s[2:3], v229, v229, 1.0
	v_rcp_f32_e32 v231, v230
	s_nop 0
	v_fma_f32 v232, -v230, v231, 1.0
	v_fmac_f32_e32 v231, v232, v231
	v_div_scale_f32 v233, vcc, 1.0, v229, 1.0
	v_mul_f32_e32 v234, v233, v231
	v_fma_f32 v235, -v230, v234, v233
	v_fmac_f32_e32 v234, v235, v231
	v_fma_f32 v230, -v230, v234, v233
	v_div_fmas_f32 v230, v230, v231, v234
	v_div_fixup_f32 v230, v230, v229, 1.0
	v_mul_f32_e32 v34, v34, v230
	v_and_b32_e32 v228, 0xffff0000, v197
	v_mul_f32_e32 v228, 0xbfb8aa3b, v228
	v_exp_f32_e32 v229, v228
	s_nop 0
	v_add_f32_e32 v229, 1.0, v229
	s_nop 0
	v_div_scale_f32 v230, s[2:3], v229, v229, 1.0
	v_rcp_f32_e32 v231, v230
	s_nop 0
	v_fma_f32 v232, -v230, v231, 1.0
	v_fmac_f32_e32 v231, v232, v231
	v_div_scale_f32 v233, vcc, 1.0, v229, 1.0
	v_mul_f32_e32 v234, v233, v231
	v_fma_f32 v235, -v230, v234, v233
	v_fmac_f32_e32 v234, v235, v231
	v_fma_f32 v230, -v230, v234, v233
	v_div_fmas_f32 v230, v230, v231, v234
	v_div_fixup_f32 v230, v230, v229, 1.0
	v_mul_f32_e32 v35, v35, v230
	v_lshlrev_b32_e32 v228, 16, v198
	v_mul_f32_e32 v228, 0xbfb8aa3b, v228
	v_exp_f32_e32 v229, v228
	s_nop 0
	v_add_f32_e32 v229, 1.0, v229
	s_nop 0
	v_div_scale_f32 v230, s[2:3], v229, v229, 1.0
	v_rcp_f32_e32 v231, v230
	s_nop 0
	v_fma_f32 v232, -v230, v231, 1.0
	v_fmac_f32_e32 v231, v232, v231
	v_div_scale_f32 v233, vcc, 1.0, v229, 1.0
	v_mul_f32_e32 v234, v233, v231
	v_fma_f32 v235, -v230, v234, v233
	v_fmac_f32_e32 v234, v235, v231
	v_fma_f32 v230, -v230, v234, v233
	v_div_fmas_f32 v230, v230, v231, v234
	v_div_fixup_f32 v230, v230, v229, 1.0
	v_mul_f32_e32 v28, v28, v230
	v_and_b32_e32 v228, 0xffff0000, v198
	v_mul_f32_e32 v228, 0xbfb8aa3b, v228
	v_exp_f32_e32 v229, v228
	s_nop 0
	v_add_f32_e32 v229, 1.0, v229
; __device__ __forceinline__ float b2f(u16 b) { return __uint_as_float(((uint32_t)b) << 16); }
; __device__ __forceinline__ float sigmoidf_(float x) { return 1.0f / (1.0f + __expf(-x)); }
; __device__ __forceinline__ void gemm_phase(const Ctx& cx, const GemmArgs& g_, char* shm) {
;     ...
;             } else {
;               const uint2 gv = *(const uint2*)(g.gate + (size_t)tok * NP + n0);
;               float v0 = sigmoidf_(b2f((u16)(gv.x & 0xffff))) * a[0], v1 = sigmoidf_(b2f((u16)(gv.x >> 16))) * a[1];
;               float v2 = sigmoidf_(b2f((u16)(gv.y & 0xffff))) * a[2], v3 = sigmoidf_(b2f((u16)(gv.y >> 16))) * a[3];
;               uint2* mp = (uint2*)(g.outb + (size_t)tok * DM + n0);
;               if (g.epi != EPI_BR0) {
;                 const uint2 pv = *mp;
;                 v0 += b2f((u16)(pv.x & 0xffff)); v1 += b2f((u16)(pv.x >> 16));
;                 v2 += b2f((u16)(pv.y & 0xffff)); v3 += b2f((u16)(pv.y >> 16));
;               }
;               uint2 o; o.x = pack2(v0, v1); o.y = pack2(v2, v3);
;               *mp = o;
;             }
	s_nop 0
	v_div_scale_f32 v230, s[2:3], v229, v229, 1.0
	v_rcp_f32_e32 v231, v230
	s_nop 0
	v_fma_f32 v232, -v230, v231, 1.0
	v_fmac_f32_e32 v231, v232, v231
	v_div_scale_f32 v233, vcc, 1.0, v229, 1.0
	v_mul_f32_e32 v234, v233, v231
	v_fma_f32 v235, -v230, v234, v233
	v_fmac_f32_e32 v234, v235, v231
	v_fma_f32 v230, -v230, v234, v233
	v_div_fmas_f32 v230, v230, v231, v234
	v_div_fixup_f32 v230, v230, v229, 1.0
	v_mul_f32_e32 v29, v29, v230
	v_lshlrev_b32_e32 v228, 16, v199
	v_mul_f32_e32 v228, 0xbfb8aa3b, v228
	v_exp_f32_e32 v229, v228
	s_nop 0
	v_add_f32_e32 v229, 1.0, v229
	s_nop 0
	v_div_scale_f32 v230, s[2:3], v229, v229, 1.0
	v_rcp_f32_e32 v231, v230
	s_nop 0
	v_fma_f32 v232, -v230, v231, 1.0
	v_fmac_f32_e32 v231, v232, v231
	v_div_scale_f32 v233, vcc, 1.0, v229, 1.0
	v_mul_f32_e32 v234, v233, v231
	v_fma_f32 v235, -v230, v234, v233
	v_fmac_f32_e32 v234, v235, v231
	v_fma_f32 v230, -v230, v234, v233
	v_div_fmas_f32 v230, v230, v231, v234
	v_div_fixup_f32 v230, v230, v229, 1.0
	v_mul_f32_e32 v30, v30, v230
	v_and_b32_e32 v228, 0xffff0000, v199
	v_mul_f32_e32 v228, 0xbfb8aa3b, v228
	v_exp_f32_e32 v229, v228
	s_nop 0
	v_add_f32_e32 v229, 1.0, v229
	s_nop 0
	v_div_scale_f32 v230, s[2:3], v229, v229, 1.0
	v_rcp_f32_e32 v231, v230
	s_nop 0
	v_fma_f32 v232, -v230, v231, 1.0
	v_fmac_f32_e32 v231, v232, v231
	v_div_scale_f32 v233, vcc, 1.0, v229, 1.0
	v_mul_f32_e32 v234, v233, v231
	v_fma_f32 v235, -v230, v234, v233
	v_fmac_f32_e32 v234, v235, v231
	v_fma_f32 v230, -v230, v234, v233
	v_div_fmas_f32 v230, v230, v231, v234
	v_div_fixup_f32 v230, v230, v229, 1.0
	v_mul_f32_e32 v31, v31, v230
	s_and_b64 vcc, exec, s[44:45]
	s_cbranch_vccz .Lmy_br_nopv_add_3_0_0
	v_lshlrev_b32_e32 v228, 16, v212
	v_add_f32_e32 v32, v32, v228
	v_and_b32_e32 v228, 0xffff0000, v212
	v_add_f32_e32 v33, v33, v228
	v_lshlrev_b32_e32 v228, 16, v213
	v_add_f32_e32 v34, v34, v228
	v_and_b32_e32 v228, 0xffff0000, v213
	v_add_f32_e32 v35, v35, v228
	v_lshlrev_b32_e32 v228, 16, v214
	v_add_f32_e32 v28, v28, v228
	v_and_b32_e32 v228, 0xffff0000, v214
	v_add_f32_e32 v29, v29, v228
	v_lshlrev_b32_e32 v228, 16, v215
	v_add_f32_e32 v30, v30, v228
	v_and_b32_e32 v228, 0xffff0000, v215
	v_add_f32_e32 v31, v31, v228
.Lmy_br_nopv_add_3_0_0:
	v_cvt_pk_bf16_f32 v236, v32, v33
	v_cvt_pk_bf16_f32 v237, v34, v35
	v_cvt_pk_bf16_f32 v238, v28, v29
	v_cvt_pk_bf16_f32 v239, v30, v31
	s_nop 1
	v_permlane16_swap_b32_e32 v236, v238
	v_permlane16_swap_b32_e32 v237, v239
	v_lshlrev_b32_e32 v228, 16, v200
	v_mul_f32_e32 v228, 0xbfb8aa3b, v228
	v_exp_f32_e32 v229, v228
	s_nop 0
	v_add_f32_e32 v229, 1.0, v229
	s_nop 0
	v_div_scale_f32 v230, s[2:3], v229, v229, 1.0
	v_rcp_f32_e32 v231, v230
	s_nop 0
	v_fma_f32 v232, -v230, v231, 1.0
	v_fmac_f32_e32 v231, v232, v231
	v_div_scale_f32 v233, vcc, 1.0, v229, 1.0
	v_mul_f32_e32 v234, v233, v231
	v_fma_f32 v235, -v230, v234, v233
	v_fmac_f32_e32 v234, v235, v231
	v_fma_f32 v230, -v230, v234, v233
	v_div_fmas_f32 v230, v230, v231, v234
	v_div_fixup_f32 v230, v230, v229, 1.0
	v_mul_f32_e32 v24, v24, v230
	v_and_b32_e32 v228, 0xffff0000, v200
	v_mul_f32_e32 v228, 0xbfb8aa3b, v228
	v_exp_f32_e32 v229, v228
	s_nop 0
	v_add_f32_e32 v229, 1.0, v229
	s_nop 0
	v_div_scale_f32 v230, s[2:3], v229, v229, 1.0
	v_rcp_f32_e32 v231, v230
	s_nop 0
	v_fma_f32 v232, -v230, v231, 1.0
	v_fmac_f32_e32 v231, v232, v231
	v_div_scale_f32 v233, vcc, 1.0, v229, 1.0
	v_mul_f32_e32 v234, v233, v231
	v_fma_f32 v235, -v230, v234, v233
	v_fmac_f32_e32 v234, v235, v231
	v_fma_f32 v230, -v230, v234, v233
	v_div_fmas_f32 v230, v230, v231, v234
	v_div_fixup_f32 v230, v230, v229, 1.0
	v_mul_f32_e32 v25, v25, v230
	v_lshlrev_b32_e32 v228, 16, v201
	v_mul_f32_e32 v228, 0xbfb8aa3b, v228
	v_exp_f32_e32 v229, v228
	s_nop 0
	v_add_f32_e32 v229, 1.0, v229
	s_nop 0
	v_div_scale_f32 v230, s[2:3], v229, v229, 1.0
	v_rcp_f32_e32 v231, v230
	s_nop 0
	v_fma_f32 v232, -v230, v231, 1.0
	v_fmac_f32_e32 v231, v232, v231
	v_div_scale_f32 v233, vcc, 1.0, v229, 1.0
	v_mul_f32_e32 v234, v233, v231
	v_fma_f32 v235, -v230, v234, v233
	v_fmac_f32_e32 v234, v235, v231
	v_fma_f32 v230, -v230, v234, v233
	v_div_fmas_f32 v230, v230, v231, v234
	v_div_fixup_f32 v230, v230, v229, 1.0
	v_mul_f32_e32 v26, v26, v230
	v_and_b32_e32 v228, 0xffff0000, v201
	v_mul_f32_e32 v228, 0xbfb8aa3b, v228
	v_exp_f32_e32 v229, v228
	s_nop 0
	v_add_f32_e32 v229, 1.0, v229
	s_nop 0
	v_div_scale_f32 v230, s[2:3], v229, v229, 1.0
	v_rcp_f32_e32 v231, v230
	s_nop 0
	v_fma_f32 v232, -v230, v231, 1.0
	v_fmac_f32_e32 v231, v232, v231
	v_div_scale_f32 v233, vcc, 1.0, v229, 1.0
	v_mul_f32_e32 v234, v233, v231
	v_fma_f32 v235, -v230, v234, v233
	v_fmac_f32_e32 v234, v235, v231
	v_fma_f32 v230, -v230, v234, v233
	v_div_fmas_f32 v230, v230, v231, v234
	v_div_fixup_f32 v230, v230, v229, 1.0
	v_mul_f32_e32 v27, v27, v230
	v_lshlrev_b32_e32 v228, 16, v202
	v_mul_f32_e32 v228, 0xbfb8aa3b, v228
	v_exp_f32_e32 v229, v228
	s_nop 0
	v_add_f32_e32 v229, 1.0, v229
	s_nop 0
	v_div_scale_f32 v230, s[2:3], v229, v229, 1.0
	v_rcp_f32_e32 v231, v230
	s_nop 0
	v_fma_f32 v232, -v230, v231, 1.0
	v_fmac_f32_e32 v231, v232, v231
	v_div_scale_f32 v233, vcc, 1.0, v229, 1.0
	v_mul_f32_e32 v234, v233, v231
	v_fma_f32 v235, -v230, v234, v233
	v_fmac_f32_e32 v234, v235, v231
	v_fma_f32 v230, -v230, v234, v233
	v_div_fmas_f32 v230, v230, v231, v234
	v_div_fixup_f32 v230, v230, v229, 1.0
	v_mul_f32_e32 v20, v20, v230
	v_and_b32_e32 v228, 0xffff0000, v202
	v_mul_f32_e32 v228, 0xbfb8aa3b, v228
	v_exp_f32_e32 v229, v228
	s_nop 0
	v_add_f32_e32 v229, 1.0, v229
	s_nop 0
	v_div_scale_f32 v230, s[2:3], v229, v229, 1.0
	v_rcp_f32_e32 v231, v230
	s_nop 0
	v_fma_f32 v232, -v230, v231, 1.0
; __device__ __forceinline__ float b2f(u16 b) { return __uint_as_float(((uint32_t)b) << 16); }
; __device__ __forceinline__ float sigmoidf_(float x) { return 1.0f / (1.0f + __expf(-x)); }
; __device__ __forceinline__ void gemm_phase(const Ctx& cx, const GemmArgs& g_, char* shm) {
;     ...
;             } else {
;               const uint2 gv = *(const uint2*)(g.gate + (size_t)tok * NP + n0);
;               float v0 = sigmoidf_(b2f((u16)(gv.x & 0xffff))) * a[0], v1 = sigmoidf_(b2f((u16)(gv.x >> 16))) * a[1];
;               float v2 = sigmoidf_(b2f((u16)(gv.y & 0xffff))) * a[2], v3 = sigmoidf_(b2f((u16)(gv.y >> 16))) * a[3];
;               uint2* mp = (uint2*)(g.outb + (size_t)tok * DM + n0);
;               if (g.epi != EPI_BR0) {
;                 const uint2 pv = *mp;
;                 v0 += b2f((u16)(pv.x & 0xffff)); v1 += b2f((u16)(pv.x >> 16));
;                 v2 += b2f((u16)(pv.y & 0xffff)); v3 += b2f((u16)(pv.y >> 16));
;               }
;               uint2 o; o.x = pack2(v0, v1); o.y = pack2(v2, v3);
;               *mp = o;
;             }
	v_fmac_f32_e32 v231, v232, v231
	v_div_scale_f32 v233, vcc, 1.0, v229, 1.0
	v_mul_f32_e32 v234, v233, v231
	v_fma_f32 v235, -v230, v234, v233
	v_fmac_f32_e32 v234, v235, v231
	v_fma_f32 v230, -v230, v234, v233
	v_div_fmas_f32 v230, v230, v231, v234
	v_div_fixup_f32 v230, v230, v229, 1.0
	v_mul_f32_e32 v21, v21, v230
	v_lshlrev_b32_e32 v228, 16, v203
	v_mul_f32_e32 v228, 0xbfb8aa3b, v228
	v_exp_f32_e32 v229, v228
	s_nop 0
	v_add_f32_e32 v229, 1.0, v229
	s_nop 0
	v_div_scale_f32 v230, s[2:3], v229, v229, 1.0
	v_rcp_f32_e32 v231, v230
	s_nop 0
	v_fma_f32 v232, -v230, v231, 1.0
	v_fmac_f32_e32 v231, v232, v231
	v_div_scale_f32 v233, vcc, 1.0, v229, 1.0
	v_mul_f32_e32 v234, v233, v231
	v_fma_f32 v235, -v230, v234, v233
	v_fmac_f32_e32 v234, v235, v231
	v_fma_f32 v230, -v230, v234, v233
	v_div_fmas_f32 v230, v230, v231, v234
	v_div_fixup_f32 v230, v230, v229, 1.0
	v_mul_f32_e32 v22, v22, v230
	v_and_b32_e32 v228, 0xffff0000, v203
	v_mul_f32_e32 v228, 0xbfb8aa3b, v228
	v_exp_f32_e32 v229, v228
	s_nop 0
	v_add_f32_e32 v229, 1.0, v229
	s_nop 0
	v_div_scale_f32 v230, s[2:3], v229, v229, 1.0
	v_rcp_f32_e32 v231, v230
	s_nop 0
	v_fma_f32 v232, -v230, v231, 1.0
	v_fmac_f32_e32 v231, v232, v231
	v_div_scale_f32 v233, vcc, 1.0, v229, 1.0
	v_mul_f32_e32 v234, v233, v231
	v_fma_f32 v235, -v230, v234, v233
	v_fmac_f32_e32 v234, v235, v231
	v_fma_f32 v230, -v230, v234, v233
	v_div_fmas_f32 v230, v230, v231, v234
	v_div_fixup_f32 v230, v230, v229, 1.0
	v_mul_f32_e32 v23, v23, v230
	s_and_b64 vcc, exec, s[44:45]
	s_cbranch_vccz .Lmy_br_nopv_add_3_0_1
	v_lshlrev_b32_e32 v228, 16, v216
	v_add_f32_e32 v24, v24, v228
	v_and_b32_e32 v228, 0xffff0000, v216
	v_add_f32_e32 v25, v25, v228
	v_lshlrev_b32_e32 v228, 16, v217
	v_add_f32_e32 v26, v26, v228
	v_and_b32_e32 v228, 0xffff0000, v217
	v_add_f32_e32 v27, v27, v228
	v_lshlrev_b32_e32 v228, 16, v218
	v_add_f32_e32 v20, v20, v228
	v_and_b32_e32 v228, 0xffff0000, v218
	v_add_f32_e32 v21, v21, v228
	v_lshlrev_b32_e32 v228, 16, v219
	v_add_f32_e32 v22, v22, v228
	v_and_b32_e32 v228, 0xffff0000, v219
	v_add_f32_e32 v23, v23, v228
.Lmy_br_nopv_add_3_0_1:
	v_cvt_pk_bf16_f32 v240, v24, v25
	v_cvt_pk_bf16_f32 v241, v26, v27
	v_cvt_pk_bf16_f32 v242, v20, v21
	v_cvt_pk_bf16_f32 v243, v22, v23
	s_nop 1
	v_permlane16_swap_b32_e32 v240, v242
	v_permlane16_swap_b32_e32 v241, v243
	v_mov_b32_e32 v244, v240
	v_mov_b32_e32 v245, v241
	v_mov_b32_e32 v246, v242
	v_mov_b32_e32 v247, v243
	v_mov_b32_dpp v240, v236 row_ror:8 row_mask:0xf bank_mask:0x3
	v_mov_b32_dpp v241, v237 row_ror:8 row_mask:0xf bank_mask:0x3
	v_mov_b32_dpp v242, v238 row_ror:8 row_mask:0xf bank_mask:0x3
	v_mov_b32_dpp v243, v239 row_ror:8 row_mask:0xf bank_mask:0x3
	v_mov_b32_dpp v236, v244 row_ror:8 row_mask:0xf bank_mask:0xc
	v_mov_b32_dpp v237, v245 row_ror:8 row_mask:0xf bank_mask:0xc
	v_mov_b32_dpp v238, v246 row_ror:8 row_mask:0xf bank_mask:0xc
	v_mov_b32_dpp v239, v247 row_ror:8 row_mask:0xf bank_mask:0xc
	global_store_dwordx4 v[188:189], v[236:239], off offset:32
	global_store_dwordx4 v[190:191], v[240:243], off offset:32
	s_nop 1
	v_lshlrev_b32_e32 v228, 16, v204
	v_mul_f32_e32 v228, 0xbfb8aa3b, v228
	v_exp_f32_e32 v229, v228
	s_nop 0
	v_add_f32_e32 v229, 1.0, v229
	s_nop 0
	v_div_scale_f32 v230, s[2:3], v229, v229, 1.0
	v_rcp_f32_e32 v231, v230
	s_nop 0
	v_fma_f32 v232, -v230, v231, 1.0
	v_fmac_f32_e32 v231, v232, v231
	v_div_scale_f32 v233, vcc, 1.0, v229, 1.0
	v_mul_f32_e32 v234, v233, v231
	v_fma_f32 v235, -v230, v234, v233
	v_fmac_f32_e32 v234, v235, v231
	v_fma_f32 v230, -v230, v234, v233
	v_div_fmas_f32 v230, v230, v231, v234
	v_div_fixup_f32 v230, v230, v229, 1.0
	v_mul_f32_e32 v16, v16, v230
	v_and_b32_e32 v228, 0xffff0000, v204
	v_mul_f32_e32 v228, 0xbfb8aa3b, v228
	v_exp_f32_e32 v229, v228
	s_nop 0
	v_add_f32_e32 v229, 1.0, v229
	s_nop 0
	v_div_scale_f32 v230, s[2:3], v229, v229, 1.0
	v_rcp_f32_e32 v231, v230
	s_nop 0
	v_fma_f32 v232, -v230, v231, 1.0
	v_fmac_f32_e32 v231, v232, v231
	v_div_scale_f32 v233, vcc, 1.0, v229, 1.0
	v_mul_f32_e32 v234, v233, v231
	v_fma_f32 v235, -v230, v234, v233
	v_fmac_f32_e32 v234, v235, v231
	v_fma_f32 v230, -v230, v234, v233
	v_div_fmas_f32 v230, v230, v231, v234
	v_div_fixup_f32 v230, v230, v229, 1.0
	v_mul_f32_e32 v17, v17, v230
	v_lshlrev_b32_e32 v228, 16, v205
	v_mul_f32_e32 v228, 0xbfb8aa3b, v228
	v_exp_f32_e32 v229, v228
	s_nop 0
	v_add_f32_e32 v229, 1.0, v229
	s_nop 0
	v_div_scale_f32 v230, s[2:3], v229, v229, 1.0
	v_rcp_f32_e32 v231, v230
	s_nop 0
	v_fma_f32 v232, -v230, v231, 1.0
	v_fmac_f32_e32 v231, v232, v231
	v_div_scale_f32 v233, vcc, 1.0, v229, 1.0
	v_mul_f32_e32 v234, v233, v231
	v_fma_f32 v235, -v230, v234, v233
	v_fmac_f32_e32 v234, v235, v231
	v_fma_f32 v230, -v230, v234, v233
	v_div_fmas_f32 v230, v230, v231, v234
	v_div_fixup_f32 v230, v230, v229, 1.0
	v_mul_f32_e32 v18, v18, v230
	v_and_b32_e32 v228, 0xffff0000, v205
	v_mul_f32_e32 v228, 0xbfb8aa3b, v228
	v_exp_f32_e32 v229, v228
	s_nop 0
	v_add_f32_e32 v229, 1.0, v229
	s_nop 0
	v_div_scale_f32 v230, s[2:3], v229, v229, 1.0
	v_rcp_f32_e32 v231, v230
	s_nop 0
	v_fma_f32 v232, -v230, v231, 1.0
	v_fmac_f32_e32 v231, v232, v231
	v_div_scale_f32 v233, vcc, 1.0, v229, 1.0
	v_mul_f32_e32 v234, v233, v231
	v_fma_f32 v235, -v230, v234, v233
	v_fmac_f32_e32 v234, v235, v231
	v_fma_f32 v230, -v230, v234, v233
	v_div_fmas_f32 v230, v230, v231, v234
	v_div_fixup_f32 v230, v230, v229, 1.0
	v_mul_f32_e32 v19, v19, v230
	v_lshlrev_b32_e32 v228, 16, v206
	v_mul_f32_e32 v228, 0xbfb8aa3b, v228
	v_exp_f32_e32 v229, v228
	s_nop 0
	v_add_f32_e32 v229, 1.0, v229
	s_nop 0
	v_div_scale_f32 v230, s[2:3], v229, v229, 1.0
	v_rcp_f32_e32 v231, v230
	s_nop 0
; __device__ __forceinline__ float b2f(u16 b) { return __uint_as_float(((uint32_t)b) << 16); }
; __device__ __forceinline__ float sigmoidf_(float x) { return 1.0f / (1.0f + __expf(-x)); }
; __device__ __forceinline__ void gemm_phase(const Ctx& cx, const GemmArgs& g_, char* shm) {
;     ...
;             } else {
;               const uint2 gv = *(const uint2*)(g.gate + (size_t)tok * NP + n0);
;               float v0 = sigmoidf_(b2f((u16)(gv.x & 0xffff))) * a[0], v1 = sigmoidf_(b2f((u16)(gv.x >> 16))) * a[1];
;               float v2 = sigmoidf_(b2f((u16)(gv.y & 0xffff))) * a[2], v3 = sigmoidf_(b2f((u16)(gv.y >> 16))) * a[3];
;               uint2* mp = (uint2*)(g.outb + (size_t)tok * DM + n0);
;               if (g.epi != EPI_BR0) {
;                 const uint2 pv = *mp;
;                 v0 += b2f((u16)(pv.x & 0xffff)); v1 += b2f((u16)(pv.x >> 16));
;                 v2 += b2f((u16)(pv.y & 0xffff)); v3 += b2f((u16)(pv.y >> 16));
;               }
;               uint2 o; o.x = pack2(v0, v1); o.y = pack2(v2, v3);
;               *mp = o;
;             }
	v_fma_f32 v232, -v230, v231, 1.0
	v_fmac_f32_e32 v231, v232, v231
	v_div_scale_f32 v233, vcc, 1.0, v229, 1.0
	v_mul_f32_e32 v234, v233, v231
	v_fma_f32 v235, -v230, v234, v233
	v_fmac_f32_e32 v234, v235, v231
	v_fma_f32 v230, -v230, v234, v233
	v_div_fmas_f32 v230, v230, v231, v234
	v_div_fixup_f32 v230, v230, v229, 1.0
	v_mul_f32_e32 v12, v12, v230
	v_and_b32_e32 v228, 0xffff0000, v206
	v_mul_f32_e32 v228, 0xbfb8aa3b, v228
	v_exp_f32_e32 v229, v228
	s_nop 0
	v_add_f32_e32 v229, 1.0, v229
	s_nop 0
	v_div_scale_f32 v230, s[2:3], v229, v229, 1.0
	v_rcp_f32_e32 v231, v230
	s_nop 0
	v_fma_f32 v232, -v230, v231, 1.0
	v_fmac_f32_e32 v231, v232, v231
	v_div_scale_f32 v233, vcc, 1.0, v229, 1.0
	v_mul_f32_e32 v234, v233, v231
	v_fma_f32 v235, -v230, v234, v233
	v_fmac_f32_e32 v234, v235, v231
	v_fma_f32 v230, -v230, v234, v233
	v_div_fmas_f32 v230, v230, v231, v234
	v_div_fixup_f32 v230, v230, v229, 1.0
	v_mul_f32_e32 v13, v13, v230
	v_lshlrev_b32_e32 v228, 16, v207
	v_mul_f32_e32 v228, 0xbfb8aa3b, v228
	v_exp_f32_e32 v229, v228
	s_nop 0
	v_add_f32_e32 v229, 1.0, v229
	s_nop 0
	v_div_scale_f32 v230, s[2:3], v229, v229, 1.0
	v_rcp_f32_e32 v231, v230
	s_nop 0
	v_fma_f32 v232, -v230, v231, 1.0
	v_fmac_f32_e32 v231, v232, v231
	v_div_scale_f32 v233, vcc, 1.0, v229, 1.0
	v_mul_f32_e32 v234, v233, v231
	v_fma_f32 v235, -v230, v234, v233
	v_fmac_f32_e32 v234, v235, v231
	v_fma_f32 v230, -v230, v234, v233
	v_div_fmas_f32 v230, v230, v231, v234
	v_div_fixup_f32 v230, v230, v229, 1.0
	v_mul_f32_e32 v14, v14, v230
	v_and_b32_e32 v228, 0xffff0000, v207
	v_mul_f32_e32 v228, 0xbfb8aa3b, v228
	v_exp_f32_e32 v229, v228
	s_nop 0
	v_add_f32_e32 v229, 1.0, v229
	s_nop 0
	v_div_scale_f32 v230, s[2:3], v229, v229, 1.0
	v_rcp_f32_e32 v231, v230
	s_nop 0
	v_fma_f32 v232, -v230, v231, 1.0
	v_fmac_f32_e32 v231, v232, v231
	v_div_scale_f32 v233, vcc, 1.0, v229, 1.0
	v_mul_f32_e32 v234, v233, v231
	v_fma_f32 v235, -v230, v234, v233
	v_fmac_f32_e32 v234, v235, v231
	v_fma_f32 v230, -v230, v234, v233
	v_div_fmas_f32 v230, v230, v231, v234
	v_div_fixup_f32 v230, v230, v229, 1.0
	v_mul_f32_e32 v15, v15, v230
	s_and_b64 vcc, exec, s[44:45]
	s_cbranch_vccz .Lmy_br_nopv_add_3_1_0
	v_lshlrev_b32_e32 v228, 16, v220
	v_add_f32_e32 v16, v16, v228
	v_and_b32_e32 v228, 0xffff0000, v220
	v_add_f32_e32 v17, v17, v228
	v_lshlrev_b32_e32 v228, 16, v221
	v_add_f32_e32 v18, v18, v228
	v_and_b32_e32 v228, 0xffff0000, v221
	v_add_f32_e32 v19, v19, v228
	v_lshlrev_b32_e32 v228, 16, v222
	v_add_f32_e32 v12, v12, v228
	v_and_b32_e32 v228, 0xffff0000, v222
	v_add_f32_e32 v13, v13, v228
	v_lshlrev_b32_e32 v228, 16, v223
	v_add_f32_e32 v14, v14, v228
	v_and_b32_e32 v228, 0xffff0000, v223
	v_add_f32_e32 v15, v15, v228
; __device__ __forceinline__ float b2f(u16 b) { return __uint_as_float(((uint32_t)b) << 16); }
; __device__ __forceinline__ float sigmoidf_(float x) { return 1.0f / (1.0f + __expf(-x)); }
; __device__ __forceinline__ void gemm_phase(const Ctx& cx, const GemmArgs& g_, char* shm) {
;     ...
;             } else {
;               const uint2 gv = *(const uint2*)(g.gate + (size_t)tok * NP + n0);
;               float v0 = sigmoidf_(b2f((u16)(gv.x & 0xffff))) * a[0], v1 = sigmoidf_(b2f((u16)(gv.x >> 16))) * a[1];
;               float v2 = sigmoidf_(b2f((u16)(gv.y & 0xffff))) * a[2], v3 = sigmoidf_(b2f((u16)(gv.y >> 16))) * a[3];
;               uint2* mp = (uint2*)(g.outb + (size_t)tok * DM + n0);
;               if (g.epi != EPI_BR0) {
;                 const uint2 pv = *mp;
;                 v0 += b2f((u16)(pv.x & 0xffff)); v1 += b2f((u16)(pv.x >> 16));
;                 v2 += b2f((u16)(pv.y & 0xffff)); v3 += b2f((u16)(pv.y >> 16));
;               }
;               uint2 o; o.x = pack2(v0, v1); o.y = pack2(v2, v3);
;               *mp = o;
;             }
.Lmy_br_nopv_add_3_1_0:
	v_cvt_pk_bf16_f32 v236, v16, v17
	v_cvt_pk_bf16_f32 v237, v18, v19
	v_cvt_pk_bf16_f32 v238, v12, v13
	v_cvt_pk_bf16_f32 v239, v14, v15
	s_nop 1
	v_permlane16_swap_b32_e32 v236, v238
	v_permlane16_swap_b32_e32 v237, v239
	v_lshlrev_b32_e32 v228, 16, v208
	v_mul_f32_e32 v228, 0xbfb8aa3b, v228
	v_exp_f32_e32 v229, v228
	s_nop 0
	v_add_f32_e32 v229, 1.0, v229
	s_nop 0
	v_div_scale_f32 v230, s[2:3], v229, v229, 1.0
	v_rcp_f32_e32 v231, v230
	s_nop 0
	v_fma_f32 v232, -v230, v231, 1.0
	v_fmac_f32_e32 v231, v232, v231
	v_div_scale_f32 v233, vcc, 1.0, v229, 1.0
	v_mul_f32_e32 v234, v233, v231
	v_fma_f32 v235, -v230, v234, v233
	v_fmac_f32_e32 v234, v235, v231
	v_fma_f32 v230, -v230, v234, v233
	v_div_fmas_f32 v230, v230, v231, v234
	v_div_fixup_f32 v230, v230, v229, 1.0
	v_mul_f32_e32 v8, v8, v230
	v_and_b32_e32 v228, 0xffff0000, v208
	v_mul_f32_e32 v228, 0xbfb8aa3b, v228
	v_exp_f32_e32 v229, v228
	s_nop 0
	v_add_f32_e32 v229, 1.0, v229
	s_nop 0
	v_div_scale_f32 v230, s[2:3], v229, v229, 1.0
	v_rcp_f32_e32 v231, v230
	s_nop 0
	v_fma_f32 v232, -v230, v231, 1.0
	v_fmac_f32_e32 v231, v232, v231
	v_div_scale_f32 v233, vcc, 1.0, v229, 1.0
	v_mul_f32_e32 v234, v233, v231
	v_fma_f32 v235, -v230, v234, v233
	v_fmac_f32_e32 v234, v235, v231
	v_fma_f32 v230, -v230, v234, v233
	v_div_fmas_f32 v230, v230, v231, v234
	v_div_fixup_f32 v230, v230, v229, 1.0
	v_mul_f32_e32 v9, v9, v230
	v_lshlrev_b32_e32 v228, 16, v209
	v_mul_f32_e32 v228, 0xbfb8aa3b, v228
	v_exp_f32_e32 v229, v228
	s_nop 0
	v_add_f32_e32 v229, 1.0, v229
	s_nop 0
	v_div_scale_f32 v230, s[2:3], v229, v229, 1.0
	v_rcp_f32_e32 v231, v230
	s_nop 0
	v_fma_f32 v232, -v230, v231, 1.0
	v_fmac_f32_e32 v231, v232, v231
	v_div_scale_f32 v233, vcc, 1.0, v229, 1.0
	v_mul_f32_e32 v234, v233, v231
	v_fma_f32 v235, -v230, v234, v233
	v_fmac_f32_e32 v234, v235, v231
	v_fma_f32 v230, -v230, v234, v233
	v_div_fmas_f32 v230, v230, v231, v234
	v_div_fixup_f32 v230, v230, v229, 1.0
	v_mul_f32_e32 v10, v10, v230
	v_and_b32_e32 v228, 0xffff0000, v209
	v_mul_f32_e32 v228, 0xbfb8aa3b, v228
	v_exp_f32_e32 v229, v228
	s_nop 0
	v_add_f32_e32 v229, 1.0, v229
	s_nop 0
	v_div_scale_f32 v230, s[2:3], v229, v229, 1.0
	v_rcp_f32_e32 v231, v230
	s_nop 0
	v_fma_f32 v232, -v230, v231, 1.0
	v_fmac_f32_e32 v231, v232, v231
	v_div_scale_f32 v233, vcc, 1.0, v229, 1.0
	v_mul_f32_e32 v234, v233, v231
	v_fma_f32 v235, -v230, v234, v233
	v_fmac_f32_e32 v234, v235, v231
	v_fma_f32 v230, -v230, v234, v233
	v_div_fmas_f32 v230, v230, v231, v234
	v_div_fixup_f32 v230, v230, v229, 1.0
	v_mul_f32_e32 v11, v11, v230
	v_lshlrev_b32_e32 v228, 16, v210
	v_mul_f32_e32 v228, 0xbfb8aa3b, v228
	v_exp_f32_e32 v229, v228
	s_nop 0
	v_add_f32_e32 v229, 1.0, v229
	s_nop 0
	v_div_scale_f32 v230, s[2:3], v229, v229, 1.0
	v_rcp_f32_e32 v231, v230
	s_nop 0
	v_fma_f32 v232, -v230, v231, 1.0
	v_fmac_f32_e32 v231, v232, v231
	v_div_scale_f32 v233, vcc, 1.0, v229, 1.0
	v_mul_f32_e32 v234, v233, v231
	v_fma_f32 v235, -v230, v234, v233
	v_fmac_f32_e32 v234, v235, v231
	v_fma_f32 v230, -v230, v234, v233
	v_div_fmas_f32 v230, v230, v231, v234
	v_div_fixup_f32 v230, v230, v229, 1.0
	v_mul_f32_e32 v4, v4, v230
	v_and_b32_e32 v228, 0xffff0000, v210
	v_mul_f32_e32 v228, 0xbfb8aa3b, v228
	v_exp_f32_e32 v229, v228
	s_nop 0
	v_add_f32_e32 v229, 1.0, v229
	s_nop 0
	v_div_scale_f32 v230, s[2:3], v229, v229, 1.0
	v_rcp_f32_e32 v231, v230
	s_nop 0
	v_fma_f32 v232, -v230, v231, 1.0
	v_fmac_f32_e32 v231, v232, v231
	v_div_scale_f32 v233, vcc, 1.0, v229, 1.0
	v_mul_f32_e32 v234, v233, v231
	v_fma_f32 v235, -v230, v234, v233
	v_fmac_f32_e32 v234, v235, v231
	v_fma_f32 v230, -v230, v234, v233
	v_div_fmas_f32 v230, v230, v231, v234
	v_div_fixup_f32 v230, v230, v229, 1.0
	v_mul_f32_e32 v5, v5, v230
	v_lshlrev_b32_e32 v228, 16, v211
	v_mul_f32_e32 v228, 0xbfb8aa3b, v228
	v_exp_f32_e32 v229, v228
	s_nop 0
	v_add_f32_e32 v229, 1.0, v229
	s_nop 0
	v_div_scale_f32 v230, s[2:3], v229, v229, 1.0
	v_rcp_f32_e32 v231, v230
	s_nop 0
	v_fma_f32 v232, -v230, v231, 1.0
	v_fmac_f32_e32 v231, v232, v231
	v_div_scale_f32 v233, vcc, 1.0, v229, 1.0
	v_mul_f32_e32 v234, v233, v231
	v_fma_f32 v235, -v230, v234, v233
	v_fmac_f32_e32 v234, v235, v231
	v_fma_f32 v230, -v230, v234, v233
	v_div_fmas_f32 v230, v230, v231, v234
	v_div_fixup_f32 v230, v230, v229, 1.0
	v_mul_f32_e32 v6, v6, v230
	v_and_b32_e32 v228, 0xffff0000, v211
	v_mul_f32_e32 v228, 0xbfb8aa3b, v228
	v_exp_f32_e32 v229, v228
	s_nop 0
	v_add_f32_e32 v229, 1.0, v229
	s_nop 0
	v_div_scale_f32 v230, s[2:3], v229, v229, 1.0
	v_rcp_f32_e32 v231, v230
	s_nop 0
	v_fma_f32 v232, -v230, v231, 1.0
	v_fmac_f32_e32 v231, v232, v231
	v_div_scale_f32 v233, vcc, 1.0, v229, 1.0
	v_mul_f32_e32 v234, v233, v231
	v_fma_f32 v235, -v230, v234, v233
	v_fmac_f32_e32 v234, v235, v231
	v_fma_f32 v230, -v230, v234, v233
	v_div_fmas_f32 v230, v230, v231, v234
	v_div_fixup_f32 v230, v230, v229, 1.0
	v_mul_f32_e32 v7, v7, v230
	s_and_b64 vcc, exec, s[44:45]
	s_cbranch_vccz .Lmy_br_nopv_add_3_1_1
	v_lshlrev_b32_e32 v228, 16, v224
	v_add_f32_e32 v8, v8, v228
	v_and_b32_e32 v228, 0xffff0000, v224
	v_add_f32_e32 v9, v9, v228
	v_lshlrev_b32_e32 v228, 16, v225
	v_add_f32_e32 v10, v10, v228
	v_and_b32_e32 v228, 0xffff0000, v225
	v_add_f32_e32 v11, v11, v228
	v_lshlrev_b32_e32 v228, 16, v226
	v_add_f32_e32 v4, v4, v228
	v_and_b32_e32 v228, 0xffff0000, v226
	v_add_f32_e32 v5, v5, v228
	v_lshlrev_b32_e32 v228, 16, v227
	v_add_f32_e32 v6, v6, v228
	v_and_b32_e32 v228, 0xffff0000, v227
	v_add_f32_e32 v7, v7, v228
.Lmy_br_nopv_add_3_1_1:
	v_cvt_pk_bf16_f32 v240, v8, v9
	v_cvt_pk_bf16_f32 v241, v10, v11
	v_cvt_pk_bf16_f32 v242, v4, v5
	v_cvt_pk_bf16_f32 v243, v6, v7
	s_nop 1
	v_permlane16_swap_b32_e32 v240, v242
	v_permlane16_swap_b32_e32 v241, v243
	v_mov_b32_e32 v244, v240
	v_mov_b32_e32 v245, v241
	v_mov_b32_e32 v246, v242
	v_mov_b32_e32 v247, v243
	v_mov_b32_dpp v240, v236 row_ror:8 row_mask:0xf bank_mask:0x3
	v_mov_b32_dpp v241, v237 row_ror:8 row_mask:0xf bank_mask:0x3
	v_mov_b32_dpp v242, v238 row_ror:8 row_mask:0xf bank_mask:0x3
	v_mov_b32_dpp v243, v239 row_ror:8 row_mask:0xf bank_mask:0x3
	v_mov_b32_dpp v236, v244 row_ror:8 row_mask:0xf bank_mask:0xc
	v_mov_b32_dpp v237, v245 row_ror:8 row_mask:0xf bank_mask:0xc
	v_mov_b32_dpp v238, v246 row_ror:8 row_mask:0xf bank_mask:0xc
	v_mov_b32_dpp v239, v247 row_ror:8 row_mask:0xf bank_mask:0xc
	global_store_dwordx4 v[188:189], v[236:239], off offset:288
	global_store_dwordx4 v[190:191], v[240:243], off offset:288
	s_nop 1
	s_branch .LBB0_231
